# GEMM mainloops: vmcnt and lgkmcnt waits before each phase barrier merged into one s_waitcnt
# baseline (speedup 1.0000x reference)
; #define PG8_STAGE(bufoff, gbase, voff) do { _Pragma("unroll") for (int _i = 0; _i < 2; ++_i) \
;         __builtin_amdgcn_global_load_lds((const unsigned*)((const char*)(gbase) + (voff)[_i]), (LAS unsigned*)(lds + (bufoff) + ldsw + _i * 8192), 16, 0, 0); } while (0)
; #define PG8_LDA(dst, b, h) do { _Pragma("unroll") for (int m = 0; m < 4; ++m) _Pragma("unroll") for (int k = 0; k < 2; ++k) dst[m][k] = *(const LAS bf16x8*)(lds + PG8_SA(b, h) + aoff + m * 2048 + k * 1024); } while (0)
; #define PG8_LDB(dst, b, h) do { _Pragma("unroll") for (int n = 0; n < 2; ++n) _Pragma("unroll") for (int k = 0; k < 2; ++k) dst[n][k] = *(const LAS bf16x8*)(lds + PG8_SB(b, h) + boff + n * 2048 + k * 1024); } while (0)
; #define PG8_MMA(ai, bj, At, Bt) do { __builtin_amdgcn_s_setprio(1); _Pragma("unroll") for (int m = 0; m < 4; ++m) _Pragma("unroll") for (int n = 0; n < 2; ++n) _Pragma("unroll") for (int k = 0; k < 2; ++k) \
;         acc[ai][bj][m][n] = __builtin_amdgcn_mfma_f32_16x16x32_bf16(Bt[n][k], At[m][k], acc[ai][bj][m][n], 0, 0, 0); __builtin_amdgcn_s_setprio(0); } while (0)
; #define PG8_WAIT_V(n) asm volatile("s_waitcnt vmcnt(" #n ")" ::: "memory")
; #define PG8_WAIT_L(n) asm volatile("s_waitcnt lgkmcnt(" #n ")" ::: "memory")
; #define PG8_BAR __builtin_amdgcn_s_barrier()
; #define PG8_SCHED __builtin_amdgcn_sched_barrier(0)
; template <class Epi, class Sched>
; __device__ __forceinline__ void gemm_phase(LAS unsigned char* lds, const Gemm g, const Sched S, const Epi E, const int tid) {
;     ...
;         for (int t = 0; t < nt; t += 2) {
;             const bool last = (t == nt - 2);
;             const char* a1 = cA + (size_t)(t + 1) * kstep;
;             const char* a2 = last ? nA : cA + (size_t)(t + 2) * kstep; const char* b2 = last ? nB : cB + (size_t)(t + 2) * kstep;
;             const char* a3 = a2 + kstep; const char* b3 = b2 + kstep;
;             PG8_LDB(B0, 0, 0); PG8_LDB(B1, 0, 1); PG8_SCHED; PG8_LDA(At, 0, 0); PG8_STAGE(PG8_SA(1, 1), a1 + hstepA, voffA);
;             PG8_WAIT_V(8); PG8_WAIT_L(0); PG8_BAR; PG8_MMA(0, 0, At, B0); PG8_MMA(0, 1, At, B1); PG8_BAR; PG8_SCHED;
;             PG8_LDA(At, 0, 1); PG8_STAGE(PG8_SB(0, 0), b2, voffB); PG8_STAGE(PG8_SB(0, 1), b2 + hstepB, voffB); PG8_STAGE(PG8_SA(0, 0), a2, voffA);
;             PG8_WAIT_V(8); PG8_WAIT_L(0); PG8_BAR; PG8_MMA(1, 0, At, B0); PG8_MMA(1, 1, At, B1); PG8_BAR; PG8_SCHED;
.LBB0_299:
	s_add_u32 s10, s22, 0xfffc0080
	s_addc_u32 s11, s23, -1
	s_add_i32 s44, 0, 0x10000
	s_cmp_eq_u32 vcc_hi, 28
	s_cselect_b32 s29, s93, s11
	s_cselect_b32 s28, s94, s10
	v_add_u32_e32 v154, s44, v167
	s_cselect_b32 s27, s95, vcc_lo
	s_cselect_b32 s26, s96, s97
	s_add_i32 s45, 0, 0x14000
	ds_read_b128 v[98:101], v154
	ds_read_b128 v[102:105], v154 offset:1024
	ds_read_b128 v[150:153], v154 offset:2048
	ds_read_b128 v[180:183], v154 offset:3072
	v_add_u32_e32 v154, s45, v167
	ds_read_b128 v[184:187], v154
	ds_read_b128 v[188:191], v154 offset:1024
	ds_read_b128 v[192:195], v154 offset:2048
	ds_read_b128 v[196:199], v154 offset:3072
	v_lshl_add_u64 v[154:155], s[22:23], 0, v[148:149]
	s_add_i32 m0, s47, 0xc000
	ds_read_b128 v[200:203], v179
	ds_read_b128 v[204:207], v179 offset:1024
	ds_read_b128 v[208:211], v179 offset:2048
	ds_read_b128 v[212:215], v179 offset:3072
	ds_read_b128 v[216:219], v179 offset:4096
	ds_read_b128 v[220:223], v179 offset:5120
	ds_read_b128 v[224:227], v179 offset:6144
	ds_read_b128 v[228:231], v179 offset:7168
	global_load_lds_dwordx4 v[154:155], off
	v_lshl_add_u64 v[154:155], s[22:23], 0, v[146:147]
	s_add_i32 m0, s47, 0xe000
	s_nop 0
	global_load_lds_dwordx4 v[154:155], off
	s_waitcnt vmcnt(8) lgkmcnt(0)
	s_barrier
	s_setprio 1
	v_mfma_f32_16x16x32_bf16 v[134:137], v[98:101], v[200:203], v[134:137]
	v_mfma_f32_16x16x32_bf16 v[130:133], v[150:153], v[200:203], v[130:133]
	v_mfma_f32_16x16x32_bf16 v[126:129], v[98:101], v[208:211], v[126:129]
	v_mfma_f32_16x16x32_bf16 v[122:125], v[150:153], v[208:211], v[122:125]
	v_mfma_f32_16x16x32_bf16 v[118:121], v[98:101], v[216:219], v[118:121]
	v_mfma_f32_16x16x32_bf16 v[114:117], v[150:153], v[216:219], v[114:117]
	v_mfma_f32_16x16x32_bf16 v[110:113], v[98:101], v[224:227], v[110:113]
	v_mfma_f32_16x16x32_bf16 v[106:109], v[150:153], v[224:227], v[106:109]
	v_mfma_f32_16x16x32_bf16 v[134:137], v[102:105], v[204:207], v[134:137]
	v_mfma_f32_16x16x32_bf16 v[130:133], v[180:183], v[204:207], v[130:133]
	v_mfma_f32_16x16x32_bf16 v[126:129], v[102:105], v[212:215], v[126:129]
	v_mfma_f32_16x16x32_bf16 v[122:125], v[180:183], v[212:215], v[122:125]
	v_mfma_f32_16x16x32_bf16 v[118:121], v[102:105], v[220:223], v[118:121]
	v_mfma_f32_16x16x32_bf16 v[114:117], v[180:183], v[220:223], v[114:117]
	v_mfma_f32_16x16x32_bf16 v[110:113], v[102:105], v[228:231], v[110:113]
	v_mfma_f32_16x16x32_bf16 v[106:109], v[180:183], v[228:231], v[106:109]
	v_mfma_f32_16x16x32_bf16 v[62:65], v[184:187], v[200:203], v[62:65]
	v_mfma_f32_16x16x32_bf16 v[58:61], v[192:195], v[200:203], v[58:61]
	v_mfma_f32_16x16x32_bf16 v[54:57], v[184:187], v[208:211], v[54:57]
	v_mfma_f32_16x16x32_bf16 v[50:53], v[192:195], v[208:211], v[50:53]
	v_mfma_f32_16x16x32_bf16 v[46:49], v[184:187], v[216:219], v[46:49]
	v_mfma_f32_16x16x32_bf16 v[42:45], v[192:195], v[216:219], v[42:45]
	v_mfma_f32_16x16x32_bf16 v[38:41], v[184:187], v[224:227], v[38:41]
	v_mfma_f32_16x16x32_bf16 v[34:37], v[192:195], v[224:227], v[34:37]
	v_mfma_f32_16x16x32_bf16 v[62:65], v[188:191], v[204:207], v[62:65]
	v_mfma_f32_16x16x32_bf16 v[58:61], v[196:199], v[204:207], v[58:61]
	v_mfma_f32_16x16x32_bf16 v[54:57], v[188:191], v[212:215], v[54:57]
	v_mfma_f32_16x16x32_bf16 v[50:53], v[196:199], v[212:215], v[50:53]
	v_mfma_f32_16x16x32_bf16 v[46:49], v[188:191], v[220:223], v[46:49]
	v_mfma_f32_16x16x32_bf16 v[42:45], v[196:199], v[220:223], v[42:45]
	v_mfma_f32_16x16x32_bf16 v[38:41], v[188:191], v[228:231], v[38:41]
	v_mfma_f32_16x16x32_bf16 v[34:37], v[196:199], v[228:231], v[34:37]
	s_setprio 0
	s_barrier
	s_add_i32 s10, s44, s46
	v_lshl_add_u64 v[154:155], s[26:27], 0, v[142:143]
	s_mov_b32 m0, s10
	ds_read_b128 v[200:203], v179 offset:16384
	ds_read_b128 v[204:207], v179 offset:17408
	ds_read_b128 v[208:211], v179 offset:18432
	ds_read_b128 v[212:215], v179 offset:19456
	ds_read_b128 v[216:219], v179 offset:20480
	ds_read_b128 v[220:223], v179 offset:21504
	ds_read_b128 v[224:227], v179 offset:22528
	ds_read_b128 v[228:231], v179 offset:23552
	global_load_lds_dwordx4 v[154:155], off
	s_add_i32 m0, s10, 0x2000
	s_add_u32 s10, s26, 0x80000
	v_lshl_add_u64 v[232:233], s[26:27], 0, v[138:139]
	s_addc_u32 s11, s27, 0
	s_add_i32 s45, s45, s46
	global_load_lds_dwordx4 v[232:233], off
	v_lshl_add_u64 v[234:235], s[10:11], 0, v[142:143]
	s_mov_b32 m0, s45
	v_lshl_add_u64 v[246:247], s[28:29], 0, v[140:141]
	global_load_lds_dwordx4 v[234:235], off
	v_lshl_add_u64 v[234:235], s[10:11], 0, v[138:139]
	s_add_i32 m0, s45, 0x2000
	s_nop 0
	global_load_lds_dwordx4 v[234:235], off
	v_lshl_add_u64 v[234:235], s[28:29], 0, v[144:145]
	s_mov_b32 m0, s47
	s_nop 0
	global_load_lds_dwordx4 v[234:235], off
	s_mov_b32 m0, s48
	s_nop 0
	global_load_lds_dwordx4 v[246:247], off
	s_waitcnt vmcnt(8) lgkmcnt(0)
	s_barrier
; #define PG8_STAGE(bufoff, gbase, voff) do { _Pragma("unroll") for (int _i = 0; _i < 2; ++_i) \
;         __builtin_amdgcn_global_load_lds((const unsigned*)((const char*)(gbase) + (voff)[_i]), (LAS unsigned*)(lds + (bufoff) + ldsw + _i * 8192), 16, 0, 0); } while (0)
; #define PG8_LDA(dst, b, h) do { _Pragma("unroll") for (int m = 0; m < 4; ++m) _Pragma("unroll") for (int k = 0; k < 2; ++k) dst[m][k] = *(const LAS bf16x8*)(lds + PG8_SA(b, h) + aoff + m * 2048 + k * 1024); } while (0)
; #define PG8_LDB(dst, b, h) do { _Pragma("unroll") for (int n = 0; n < 2; ++n) _Pragma("unroll") for (int k = 0; k < 2; ++k) dst[n][k] = *(const LAS bf16x8*)(lds + PG8_SB(b, h) + boff + n * 2048 + k * 1024); } while (0)
; #define PG8_MMA(ai, bj, At, Bt) do { __builtin_amdgcn_s_setprio(1); _Pragma("unroll") for (int m = 0; m < 4; ++m) _Pragma("unroll") for (int n = 0; n < 2; ++n) _Pragma("unroll") for (int k = 0; k < 2; ++k) \
;         acc[ai][bj][m][n] = __builtin_amdgcn_mfma_f32_16x16x32_bf16(Bt[n][k], At[m][k], acc[ai][bj][m][n], 0, 0, 0); __builtin_amdgcn_s_setprio(0); } while (0)
; #define PG8_WAIT_V(n) asm volatile("s_waitcnt vmcnt(" #n ")" ::: "memory")
; #define PG8_WAIT_L(n) asm volatile("s_waitcnt lgkmcnt(" #n ")" ::: "memory")
; #define PG8_BAR __builtin_amdgcn_s_barrier()
; #define PG8_SCHED __builtin_amdgcn_sched_barrier(0)
; template <class Epi, class Sched>
; __device__ __forceinline__ void gemm_phase(LAS unsigned char* lds, const Gemm g, const Sched S, const Epi E, const int tid) {
;     ...
;             PG8_WAIT_V(8); PG8_WAIT_L(0); PG8_BAR; PG8_MMA(1, 0, At, B0); PG8_MMA(1, 1, At, B1); PG8_BAR; PG8_SCHED;
;             PG8_LDB(B0, 1, 0); PG8_LDB(B1, 1, 1); PG8_SCHED; PG8_LDA(At, 1, 0); PG8_STAGE(PG8_SA(0, 1), a2 + hstepA, voffA);
;             PG8_WAIT_V(8); PG8_WAIT_L(0); PG8_BAR; PG8_MMA(0, 0, At, B0); PG8_MMA(0, 1, At, B1); PG8_BAR; PG8_SCHED;
	s_setprio 1
	v_mfma_f32_16x16x32_bf16 v[94:97], v[98:101], v[200:203], v[94:97]
	v_mfma_f32_16x16x32_bf16 v[90:93], v[150:153], v[200:203], v[90:93]
	v_mfma_f32_16x16x32_bf16 v[86:89], v[98:101], v[208:211], v[86:89]
	v_mfma_f32_16x16x32_bf16 v[82:85], v[150:153], v[208:211], v[82:85]
	v_mfma_f32_16x16x32_bf16 v[78:81], v[98:101], v[216:219], v[78:81]
	v_mfma_f32_16x16x32_bf16 v[74:77], v[150:153], v[216:219], v[74:77]
	v_mfma_f32_16x16x32_bf16 v[70:73], v[98:101], v[224:227], v[70:73]
	v_mfma_f32_16x16x32_bf16 v[66:69], v[150:153], v[224:227], v[66:69]
	v_mfma_f32_16x16x32_bf16 v[94:97], v[102:105], v[204:207], v[94:97]
	v_mfma_f32_16x16x32_bf16 v[90:93], v[180:183], v[204:207], v[90:93]
	v_mfma_f32_16x16x32_bf16 v[86:89], v[102:105], v[212:215], v[86:89]
	v_mfma_f32_16x16x32_bf16 v[82:85], v[180:183], v[212:215], v[82:85]
	v_mfma_f32_16x16x32_bf16 v[78:81], v[102:105], v[220:223], v[78:81]
	v_mfma_f32_16x16x32_bf16 v[74:77], v[180:183], v[220:223], v[74:77]
	v_mfma_f32_16x16x32_bf16 v[70:73], v[102:105], v[228:231], v[70:73]
	v_mfma_f32_16x16x32_bf16 v[66:69], v[180:183], v[228:231], v[66:69]
	v_mfma_f32_16x16x32_bf16 v[30:33], v[184:187], v[200:203], v[30:33]
	v_mfma_f32_16x16x32_bf16 v[26:29], v[192:195], v[200:203], v[26:29]
	v_mfma_f32_16x16x32_bf16 v[22:25], v[184:187], v[208:211], v[22:25]
	v_mfma_f32_16x16x32_bf16 v[18:21], v[192:195], v[208:211], v[18:21]
	v_mfma_f32_16x16x32_bf16 v[14:17], v[184:187], v[216:219], v[14:17]
	v_mfma_f32_16x16x32_bf16 v[10:13], v[192:195], v[216:219], v[10:13]
	v_mfma_f32_16x16x32_bf16 v[6:9], v[184:187], v[224:227], v[6:9]
	v_mfma_f32_16x16x32_bf16 v[2:5], v[192:195], v[224:227], v[2:5]
	v_mfma_f32_16x16x32_bf16 v[30:33], v[188:191], v[204:207], v[30:33]
	v_mfma_f32_16x16x32_bf16 v[26:29], v[196:199], v[204:207], v[26:29]
	v_mfma_f32_16x16x32_bf16 v[22:25], v[188:191], v[212:215], v[22:25]
	v_mfma_f32_16x16x32_bf16 v[18:21], v[196:199], v[212:215], v[18:21]
	v_mfma_f32_16x16x32_bf16 v[14:17], v[188:191], v[220:223], v[14:17]
	v_mfma_f32_16x16x32_bf16 v[10:13], v[196:199], v[220:223], v[10:13]
	v_mfma_f32_16x16x32_bf16 v[6:9], v[188:191], v[228:231], v[6:9]
	v_mfma_f32_16x16x32_bf16 v[2:5], v[196:199], v[228:231], v[2:5]
	s_setprio 0
	s_barrier
	s_add_i32 s45, 0, 0x18000
	s_add_i32 s6, 0, 0x1c000
	v_add_u32_e32 v180, s45, v167
	v_add_u32_e32 v196, s6, v167
	ds_read_b128 v[98:101], v180
	ds_read_b128 v[102:105], v180 offset:1024
	ds_read_b128 v[150:153], v180 offset:2048
	ds_read_b128 v[180:183], v180 offset:3072
	ds_read_b128 v[184:187], v196
	ds_read_b128 v[188:191], v196 offset:1024
	ds_read_b128 v[192:195], v196 offset:2048
	ds_read_b128 v[196:199], v196 offset:3072
	s_add_u32 s10, s28, 0x40000
	s_addc_u32 s11, s29, 0
	s_mov_b32 m0, s49
	v_lshl_add_u64 v[248:249], s[10:11], 0, v[144:145]
	ds_read_b128 v[200:203], v179 offset:32768
	ds_read_b128 v[204:207], v179 offset:33792
	ds_read_b128 v[208:211], v179 offset:34816
	ds_read_b128 v[212:215], v179 offset:35840
	ds_read_b128 v[216:219], v179 offset:36864
	ds_read_b128 v[220:223], v179 offset:37888
	ds_read_b128 v[224:227], v179 offset:38912
	ds_read_b128 v[228:231], v179 offset:39936
	global_load_lds_dwordx4 v[248:249], off
	v_lshl_add_u64 v[248:249], s[10:11], 0, v[140:141]
	s_mov_b32 m0, s62
	s_nop 0
	global_load_lds_dwordx4 v[248:249], off
	s_waitcnt vmcnt(8) lgkmcnt(0)
	s_barrier
	s_setprio 1
	v_mfma_f32_16x16x32_bf16 v[134:137], v[98:101], v[200:203], v[134:137]
	v_mfma_f32_16x16x32_bf16 v[130:133], v[150:153], v[200:203], v[130:133]
	v_mfma_f32_16x16x32_bf16 v[126:129], v[98:101], v[208:211], v[126:129]
	v_mfma_f32_16x16x32_bf16 v[122:125], v[150:153], v[208:211], v[122:125]
	v_mfma_f32_16x16x32_bf16 v[118:121], v[98:101], v[216:219], v[118:121]
	v_mfma_f32_16x16x32_bf16 v[114:117], v[150:153], v[216:219], v[114:117]
	v_mfma_f32_16x16x32_bf16 v[110:113], v[98:101], v[224:227], v[110:113]
	v_mfma_f32_16x16x32_bf16 v[106:109], v[150:153], v[224:227], v[106:109]
	v_mfma_f32_16x16x32_bf16 v[134:137], v[102:105], v[204:207], v[134:137]
	v_mfma_f32_16x16x32_bf16 v[130:133], v[180:183], v[204:207], v[130:133]
	v_mfma_f32_16x16x32_bf16 v[126:129], v[102:105], v[212:215], v[126:129]
	v_mfma_f32_16x16x32_bf16 v[122:125], v[180:183], v[212:215], v[122:125]
	v_mfma_f32_16x16x32_bf16 v[118:121], v[102:105], v[220:223], v[118:121]
	v_mfma_f32_16x16x32_bf16 v[114:117], v[180:183], v[220:223], v[114:117]
	v_mfma_f32_16x16x32_bf16 v[110:113], v[102:105], v[228:231], v[110:113]
	v_mfma_f32_16x16x32_bf16 v[106:109], v[180:183], v[228:231], v[106:109]
	v_mfma_f32_16x16x32_bf16 v[62:65], v[184:187], v[200:203], v[62:65]
	v_mfma_f32_16x16x32_bf16 v[58:61], v[192:195], v[200:203], v[58:61]
	v_mfma_f32_16x16x32_bf16 v[54:57], v[184:187], v[208:211], v[54:57]
	v_mfma_f32_16x16x32_bf16 v[50:53], v[192:195], v[208:211], v[50:53]
	v_mfma_f32_16x16x32_bf16 v[46:49], v[184:187], v[216:219], v[46:49]
	v_mfma_f32_16x16x32_bf16 v[42:45], v[192:195], v[216:219], v[42:45]
	v_mfma_f32_16x16x32_bf16 v[38:41], v[184:187], v[224:227], v[38:41]
	v_mfma_f32_16x16x32_bf16 v[34:37], v[192:195], v[224:227], v[34:37]
	v_mfma_f32_16x16x32_bf16 v[62:65], v[188:191], v[204:207], v[62:65]
	v_mfma_f32_16x16x32_bf16 v[58:61], v[196:199], v[204:207], v[58:61]
	v_mfma_f32_16x16x32_bf16 v[54:57], v[188:191], v[212:215], v[54:57]
	v_mfma_f32_16x16x32_bf16 v[50:53], v[196:199], v[212:215], v[50:53]
	v_mfma_f32_16x16x32_bf16 v[46:49], v[188:191], v[220:223], v[46:49]
	v_mfma_f32_16x16x32_bf16 v[42:45], v[196:199], v[220:223], v[42:45]
	v_mfma_f32_16x16x32_bf16 v[38:41], v[188:191], v[228:231], v[38:41]
	v_mfma_f32_16x16x32_bf16 v[34:37], v[196:199], v[228:231], v[34:37]
	s_setprio 0
	s_barrier
; #define PG8_STAGE(bufoff, gbase, voff) do { _Pragma("unroll") for (int _i = 0; _i < 2; ++_i) \
;         __builtin_amdgcn_global_load_lds((const unsigned*)((const char*)(gbase) + (voff)[_i]), (LAS unsigned*)(lds + (bufoff) + ldsw + _i * 8192), 16, 0, 0); } while (0)
; #define PG8_LDA(dst, b, h) do { _Pragma("unroll") for (int m = 0; m < 4; ++m) _Pragma("unroll") for (int k = 0; k < 2; ++k) dst[m][k] = *(const LAS bf16x8*)(lds + PG8_SA(b, h) + aoff + m * 2048 + k * 1024); } while (0)
; #define PG8_MMA(ai, bj, At, Bt) do { __builtin_amdgcn_s_setprio(1); _Pragma("unroll") for (int m = 0; m < 4; ++m) _Pragma("unroll") for (int n = 0; n < 2; ++n) _Pragma("unroll") for (int k = 0; k < 2; ++k) \
;         acc[ai][bj][m][n] = __builtin_amdgcn_mfma_f32_16x16x32_bf16(Bt[n][k], At[m][k], acc[ai][bj][m][n], 0, 0, 0); __builtin_amdgcn_s_setprio(0); } while (0)
; #define PG8_WAIT_V(n) asm volatile("s_waitcnt vmcnt(" #n ")" ::: "memory")
; #define PG8_WAIT_L(n) asm volatile("s_waitcnt lgkmcnt(" #n ")" ::: "memory")
; #define PG8_BAR __builtin_amdgcn_s_barrier()
; #define PG8_SCHED __builtin_amdgcn_sched_barrier(0)
; template <class Epi, class Sched>
; __device__ __forceinline__ void gemm_phase(LAS unsigned char* lds, const Gemm g, const Sched S, const Epi E, const int tid) {
;     ...
;             PG8_LDA(At, 1, 1); PG8_STAGE(PG8_SB(1, 0), b3, voffB); PG8_STAGE(PG8_SB(1, 1), b3 + hstepB, voffB); PG8_STAGE(PG8_SA(1, 0), a3, voffA);
;             PG8_WAIT_V(8); PG8_WAIT_L(0); PG8_BAR; PG8_MMA(1, 0, At, B0); PG8_MMA(1, 1, At, B1); PG8_BAR; PG8_SCHED;
;         }
	s_add_i32 s7, s45, s46
	v_lshl_add_u64 v[154:155], v[154:155], 0, s[64:65]
	s_mov_b32 m0, s7
	ds_read_b128 v[200:203], v179 offset:49152
	ds_read_b128 v[204:207], v179 offset:50176
	ds_read_b128 v[208:211], v179 offset:51200
	ds_read_b128 v[212:215], v179 offset:52224
	ds_read_b128 v[216:219], v179 offset:53248
	ds_read_b128 v[220:223], v179 offset:54272
	ds_read_b128 v[224:227], v179 offset:55296
	ds_read_b128 v[228:231], v179 offset:56320
	global_load_lds_dwordx4 v[154:155], off
	s_add_i32 m0, s7, 0x2000
	s_add_u32 s10, s26, 0x80080
	v_lshl_add_u64 v[154:155], v[232:233], 0, s[64:65]
	s_addc_u32 s11, s27, 0
	s_add_i32 s6, s6, s46
	global_load_lds_dwordx4 v[154:155], off
	v_lshl_add_u64 v[154:155], s[10:11], 0, v[142:143]
	s_mov_b32 m0, s6
	s_nop 0
	global_load_lds_dwordx4 v[154:155], off
	v_lshl_add_u64 v[154:155], s[10:11], 0, v[138:139]
	s_add_i32 m0, s6, 0x2000
	s_nop 0
	global_load_lds_dwordx4 v[154:155], off
	v_lshl_add_u64 v[154:155], v[234:235], 0, s[64:65]
	s_mov_b32 m0, s84
	s_nop 0
	global_load_lds_dwordx4 v[154:155], off
	v_lshl_add_u64 v[154:155], v[246:247], 0, s[64:65]
	s_mov_b32 m0, s85
	s_nop 0
	global_load_lds_dwordx4 v[154:155], off
	s_waitcnt vmcnt(8) lgkmcnt(0)
	s_barrier
	s_setprio 1
	v_mfma_f32_16x16x32_bf16 v[94:97], v[98:101], v[200:203], v[94:97]
	v_mfma_f32_16x16x32_bf16 v[90:93], v[150:153], v[200:203], v[90:93]
	v_mfma_f32_16x16x32_bf16 v[86:89], v[98:101], v[208:211], v[86:89]
	v_mfma_f32_16x16x32_bf16 v[82:85], v[150:153], v[208:211], v[82:85]
	v_mfma_f32_16x16x32_bf16 v[78:81], v[98:101], v[216:219], v[78:81]
	v_mfma_f32_16x16x32_bf16 v[74:77], v[150:153], v[216:219], v[74:77]
	v_mfma_f32_16x16x32_bf16 v[70:73], v[98:101], v[224:227], v[70:73]
	v_mfma_f32_16x16x32_bf16 v[66:69], v[150:153], v[224:227], v[66:69]
	v_mfma_f32_16x16x32_bf16 v[94:97], v[102:105], v[204:207], v[94:97]
	v_mfma_f32_16x16x32_bf16 v[90:93], v[180:183], v[204:207], v[90:93]
	v_mfma_f32_16x16x32_bf16 v[86:89], v[102:105], v[212:215], v[86:89]
	v_mfma_f32_16x16x32_bf16 v[82:85], v[180:183], v[212:215], v[82:85]
	v_mfma_f32_16x16x32_bf16 v[78:81], v[102:105], v[220:223], v[78:81]
	v_mfma_f32_16x16x32_bf16 v[74:77], v[180:183], v[220:223], v[74:77]
	v_mfma_f32_16x16x32_bf16 v[70:73], v[102:105], v[228:231], v[70:73]
	v_mfma_f32_16x16x32_bf16 v[66:69], v[180:183], v[228:231], v[66:69]
	v_mfma_f32_16x16x32_bf16 v[30:33], v[184:187], v[200:203], v[30:33]
	v_mfma_f32_16x16x32_bf16 v[26:29], v[192:195], v[200:203], v[26:29]
	v_mfma_f32_16x16x32_bf16 v[22:25], v[184:187], v[208:211], v[22:25]
	v_mfma_f32_16x16x32_bf16 v[18:21], v[192:195], v[208:211], v[18:21]
	v_mfma_f32_16x16x32_bf16 v[14:17], v[184:187], v[216:219], v[14:17]
	v_mfma_f32_16x16x32_bf16 v[10:13], v[192:195], v[216:219], v[10:13]
	v_mfma_f32_16x16x32_bf16 v[6:9], v[184:187], v[224:227], v[6:9]
	v_mfma_f32_16x16x32_bf16 v[2:5], v[192:195], v[224:227], v[2:5]
	v_mfma_f32_16x16x32_bf16 v[30:33], v[188:191], v[204:207], v[30:33]
	v_mfma_f32_16x16x32_bf16 v[26:29], v[196:199], v[204:207], v[26:29]
	v_mfma_f32_16x16x32_bf16 v[22:25], v[188:191], v[212:215], v[22:25]
	v_mfma_f32_16x16x32_bf16 v[18:21], v[196:199], v[212:215], v[18:21]
	v_mfma_f32_16x16x32_bf16 v[14:17], v[188:191], v[220:223], v[14:17]
	v_mfma_f32_16x16x32_bf16 v[10:13], v[196:199], v[220:223], v[10:13]
	v_mfma_f32_16x16x32_bf16 v[6:9], v[188:191], v[228:231], v[6:9]
	v_mfma_f32_16x16x32_bf16 v[2:5], v[196:199], v[228:231], v[2:5]
	s_setprio 0
	s_barrier
	s_add_i32 vcc_hi, vcc_hi, 2
	s_add_u32 s97, s97, 0x100
	s_addc_u32 vcc_lo, vcc_lo, 0
	s_add_u32 s22, s22, 0x100
	s_addc_u32 s23, s23, 0
	s_cmp_gt_u32 vcc_hi, 29
	s_cbranch_scc0 .LBB0_299
	s_and_b64 vcc, exec, s[18:19]
	s_cbranch_vccz .LBB0_302
	s_barrier

;     __host__ __device__ bool next(int i, Unit& u) const { const int L = i * G + c; if (L >= 32) return false; u.pm = L; u.pn = L >> 4; return true; }
; #define PG8_STAGE(bufoff, gbase, voff) do { _Pragma("unroll") for (int _i = 0; _i < 2; ++_i) \
;         __builtin_amdgcn_global_load_lds((const unsigned*)((const char*)(gbase) + (voff)[_i]), (LAS unsigned*)(lds + (bufoff) + ldsw + _i * 8192), 16, 0, 0); } while (0)
; #define PG8_LDA(dst, b, h) do { _Pragma("unroll") for (int m = 0; m < 4; ++m) _Pragma("unroll") for (int k = 0; k < 2; ++k) dst[m][k] = *(const LAS bf16x8*)(lds + PG8_SA(b, h) + aoff + m * 2048 + k * 1024); } while (0)
; #define PG8_LDB(dst, b, h) do { _Pragma("unroll") for (int n = 0; n < 2; ++n) _Pragma("unroll") for (int k = 0; k < 2; ++k) dst[n][k] = *(const LAS bf16x8*)(lds + PG8_SB(b, h) + boff + n * 2048 + k * 1024); } while (0)
; template <class Epi, class Sched>
; __device__ __forceinline__ void gemm_phase(LAS unsigned char* lds, const Gemm g, const Sched S, const Epi E, const int tid) {
;     ...
;         const bool has_next = S.next(ui + 1, nxt);
;         const char* nA = has_next ? (const char*)g.A + (size_t)nxt.pm * tstepA : cA; const char* nB = has_next ? (const char*)g.Bt + (size_t)nxt.pn * tstepB : cB;
;         for (int t = 0; t < nt; t += 2) {
;             const bool last = (t == nt - 2);
;             const char* a1 = cA + (size_t)(t + 1) * kstep;
;             const char* a2 = last ? nA : cA + (size_t)(t + 2) * kstep; const char* b2 = last ? nB : cB + (size_t)(t + 2) * kstep;
;             const char* a3 = a2 + kstep; const char* b3 = b2 + kstep;
;             PG8_LDB(B0, 0, 0); PG8_LDB(B1, 0, 1); PG8_SCHED; PG8_LDA(At, 0, 0); PG8_STAGE(PG8_SA(1, 1), a1 + hstepA, voffA);
;             PG8_WAIT_V(8); PG8_WAIT_L(0); PG8_BAR; PG8_MMA(0, 0, At, B0); PG8_MMA(0, 1, At, B1); PG8_BAR; PG8_SCHED;
;             PG8_LDA(At, 0, 1); PG8_STAGE(PG8_SB(0, 0), b2, voffB); PG8_STAGE(PG8_SB(0, 1), b2 + hstepB, voffB); PG8_STAGE(PG8_SA(0, 0), a2, voffA);
;             PG8_WAIT_V(8); PG8_WAIT_L(0); PG8_BAR; PG8_MMA(1, 0, At, B0); PG8_MMA(1, 1, At, B1); PG8_BAR; PG8_SCHED;
;             PG8_LDB(B0, 1, 0); PG8_LDB(B1, 1, 1); PG8_SCHED; PG8_LDA(At, 1, 0); PG8_STAGE(PG8_SA(0, 1), a2 + hstepA, voffA);
;             PG8_WAIT_V(8); PG8_WAIT_L(0); PG8_BAR; PG8_MMA(0, 0, At, B0); PG8_MMA(0, 1, At, B1); PG8_BAR; PG8_SCHED;
.LBB0_310:
	s_mov_b32 s6, s92
	s_ashr_i32 s92, s89, 4
	s_cmp_lt_i32 s89, 32
	s_mov_b64 s[42:43], s[4:5]
	s_cselect_b64 s[4:5], -1, 0
	s_and_b64 s[4:5], s[4:5], exec
	s_cselect_b32 s4, s92, s6
	s_ashr_i32 s5, s4, 31
	s_lshl_b64 s[4:5], s[4:5], 17
	s_add_u32 s4, s25, s4
	s_addc_u32 s5, s46, s5
	s_cmp_lt_i32 s89, 32
	s_cselect_b64 s[10:11], -1, 0
	s_and_b64 s[10:11], s[10:11], exec
	s_cselect_b32 s10, s89, s93
	v_add_u32_e32 v130, s44, v70
	s_cselect_b32 s26, s4, s42
	s_cselect_b32 s27, s5, s43
	s_ashr_i32 s11, s10, 31
	ds_read_b128 v[2:5], v130
	ds_read_b128 v[6:9], v130 offset:1024
	ds_read_b128 v[10:13], v130 offset:2048
	ds_read_b128 v[14:17], v130 offset:3072
	s_lshl_b64 s[10:11], s[10:11], 17
	s_mov_b64 s[40:41], s[16:17]
	s_add_u32 s16, s8, s10
	s_addc_u32 s17, s9, s11
	s_cmp_lt_i32 s89, 32
	s_cselect_b64 s[22:23], -1, 0
	s_and_b64 s[10:11], s[22:23], exec
	s_cselect_b32 s29, s17, s41
	s_cselect_b32 s28, s16, s40
	s_add_u32 s10, s40, 0x10080
	s_addc_u32 s11, s41, 0
	s_add_i32 s97, s37, 0xc000
	v_lshl_add_u64 v[50:51], s[10:11], 0, v[68:69]
	s_mov_b32 m0, s97
	s_add_i32 s13, s37, 0xe000
	ds_read_b128 v[18:21], v71
	ds_read_b128 v[22:25], v71 offset:1024
	ds_read_b128 v[26:29], v71 offset:2048
	ds_read_b128 v[30:33], v71 offset:3072
	ds_read_b128 v[34:37], v71 offset:4096
	ds_read_b128 v[38:41], v71 offset:5120
	ds_read_b128 v[42:45], v71 offset:6144
	ds_read_b128 v[46:49], v71 offset:7168
	global_load_lds_dwordx4 v[50:51], off
	v_lshl_add_u64 v[50:51], s[10:11], 0, v[66:67]
	s_mov_b32 m0, s13
	s_nop 0
	global_load_lds_dwordx4 v[50:51], off
	s_waitcnt vmcnt(8) lgkmcnt(0)
	s_barrier
	s_setprio 1
	v_mfma_f32_16x16x32_bf16 v[50:53], v[2:5], v[18:21], 0
	v_mfma_f32_16x16x32_bf16 v[18:21], v[10:13], v[18:21], 0
	v_mfma_f32_16x16x32_bf16 v[50:53], v[6:9], v[22:25], v[50:53]
	v_mfma_f32_16x16x32_bf16 v[18:21], v[14:17], v[22:25], v[18:21]
	v_mfma_f32_16x16x32_bf16 v[22:25], v[2:5], v[26:29], 0
	v_mfma_f32_16x16x32_bf16 v[26:29], v[10:13], v[26:29], 0
	v_mfma_f32_16x16x32_bf16 v[22:25], v[6:9], v[30:33], v[22:25]
	v_mfma_f32_16x16x32_bf16 v[26:29], v[14:17], v[30:33], v[26:29]
	v_mfma_f32_16x16x32_bf16 v[30:33], v[2:5], v[34:37], 0
	v_mfma_f32_16x16x32_bf16 v[34:37], v[10:13], v[34:37], 0
	v_mfma_f32_16x16x32_bf16 v[30:33], v[6:9], v[38:41], v[30:33]
	v_mfma_f32_16x16x32_bf16 v[34:37], v[14:17], v[38:41], v[34:37]
	v_mfma_f32_16x16x32_bf16 v[38:41], v[2:5], v[42:45], 0
	v_mfma_f32_16x16x32_bf16 v[42:45], v[10:13], v[42:45], 0
	v_mfma_f32_16x16x32_bf16 v[38:41], v[6:9], v[46:49], v[38:41]
	v_mfma_f32_16x16x32_bf16 v[42:45], v[14:17], v[46:49], v[42:45]
	s_setprio 0
	s_barrier
	s_add_i32 s96, s44, s47
	v_lshl_add_u64 v[120:121], s[42:43], 0, v[68:69]
	s_mov_b64 s[6:7], 0x100
	s_add_i32 s94, s96, 0x2000
	v_lshl_add_u64 v[88:89], v[120:121], 0, s[6:7]
	s_mov_b32 m0, s96
	v_lshl_add_u64 v[122:123], s[42:43], 0, v[66:67]
	s_add_u32 s10, s42, 0x10100
	ds_read_b128 v[46:49], v71 offset:16384
	ds_read_b128 v[54:57], v71 offset:17408
	ds_read_b128 v[58:61], v71 offset:18432
	ds_read_b128 v[62:65], v71 offset:19456
	ds_read_b128 v[72:75], v71 offset:20480
	ds_read_b128 v[76:79], v71 offset:21504
	ds_read_b128 v[80:83], v71 offset:22528
	ds_read_b128 v[84:87], v71 offset:23552
	global_load_lds_dwordx4 v[88:89], off
	v_lshl_add_u64 v[88:89], v[122:123], 0, s[6:7]
	s_mov_b32 m0, s94
	s_addc_u32 s11, s43, 0
	global_load_lds_dwordx4 v[88:89], off
	v_lshl_add_u64 v[88:89], s[10:11], 0, v[68:69]
	s_mov_b32 m0, s48
	v_lshl_add_u64 v[124:125], s[40:41], 0, v[68:69]
	global_load_lds_dwordx4 v[88:89], off
	v_lshl_add_u64 v[88:89], s[10:11], 0, v[66:67]
	s_mov_b32 m0, s49
	v_lshl_add_u64 v[126:127], s[40:41], 0, v[66:67]
	global_load_lds_dwordx4 v[88:89], off
	v_lshl_add_u64 v[88:89], v[124:125], 0, s[6:7]
	s_mov_b32 m0, s37
	s_nop 0
	global_load_lds_dwordx4 v[88:89], off
	v_lshl_add_u64 v[88:89], v[126:127], 0, s[6:7]
	s_mov_b32 m0, s62
	s_nop 0
	global_load_lds_dwordx4 v[88:89], off
	s_waitcnt vmcnt(8) lgkmcnt(0)
	s_barrier
	s_setprio 1
	v_mfma_f32_16x16x32_bf16 v[88:91], v[2:5], v[46:49], 0
	v_mfma_f32_16x16x32_bf16 v[46:49], v[10:13], v[46:49], 0
	v_mfma_f32_16x16x32_bf16 v[88:91], v[6:9], v[54:57], v[88:91]
	v_mfma_f32_16x16x32_bf16 v[46:49], v[14:17], v[54:57], v[46:49]
	v_mfma_f32_16x16x32_bf16 v[54:57], v[2:5], v[58:61], 0
	v_mfma_f32_16x16x32_bf16 v[58:61], v[10:13], v[58:61], 0
	v_mfma_f32_16x16x32_bf16 v[54:57], v[6:9], v[62:65], v[54:57]
	v_mfma_f32_16x16x32_bf16 v[58:61], v[14:17], v[62:65], v[58:61]
	v_mfma_f32_16x16x32_bf16 v[62:65], v[2:5], v[72:75], 0
	v_mfma_f32_16x16x32_bf16 v[2:5], v[2:5], v[80:83], 0
	v_mfma_f32_16x16x32_bf16 v[62:65], v[6:9], v[76:79], v[62:65]
	v_mfma_f32_16x16x32_bf16 v[2:5], v[6:9], v[84:87], v[2:5]
	v_mfma_f32_16x16x32_bf16 v[6:9], v[10:13], v[80:83], 0
	v_mfma_f32_16x16x32_bf16 v[72:75], v[10:13], v[72:75], 0
	v_mfma_f32_16x16x32_bf16 v[6:9], v[14:17], v[84:87], v[6:9]
	v_mfma_f32_16x16x32_bf16 v[72:75], v[14:17], v[76:79], v[72:75]
	s_setprio 0
	s_barrier
	v_add_u32_e32 v131, s45, v70
	ds_read_b128 v[10:13], v131
	ds_read_b128 v[14:17], v131 offset:1024
	ds_read_b128 v[76:79], v131 offset:2048
	ds_read_b128 v[80:83], v131 offset:3072
	s_add_u32 s10, s40, 0x10100
	s_addc_u32 s11, s41, 0
	s_mov_b32 m0, s68
	v_lshl_add_u64 v[128:129], s[10:11], 0, v[68:69]
	ds_read_b128 v[84:87], v71 offset:32768
	ds_read_b128 v[92:95], v71 offset:33792
	ds_read_b128 v[96:99], v71 offset:34816
	ds_read_b128 v[100:103], v71 offset:35840
	ds_read_b128 v[104:107], v71 offset:36864
	ds_read_b128 v[108:111], v71 offset:37888
	ds_read_b128 v[112:115], v71 offset:38912
	ds_read_b128 v[116:119], v71 offset:39936
	global_load_lds_dwordx4 v[128:129], off
	v_lshl_add_u64 v[128:129], s[10:11], 0, v[66:67]
	s_mov_b32 m0, s69
	s_nop 0
	global_load_lds_dwordx4 v[128:129], off
	s_waitcnt vmcnt(8) lgkmcnt(0)
	s_barrier
; #define PG8_STAGE(bufoff, gbase, voff) do { _Pragma("unroll") for (int _i = 0; _i < 2; ++_i) \
;         __builtin_amdgcn_global_load_lds((const unsigned*)((const char*)(gbase) + (voff)[_i]), (LAS unsigned*)(lds + (bufoff) + ldsw + _i * 8192), 16, 0, 0); } while (0)
; #define PG8_LDA(dst, b, h) do { _Pragma("unroll") for (int m = 0; m < 4; ++m) _Pragma("unroll") for (int k = 0; k < 2; ++k) dst[m][k] = *(const LAS bf16x8*)(lds + PG8_SA(b, h) + aoff + m * 2048 + k * 1024); } while (0)
; #define PG8_LDB(dst, b, h) do { _Pragma("unroll") for (int n = 0; n < 2; ++n) _Pragma("unroll") for (int k = 0; k < 2; ++k) dst[n][k] = *(const LAS bf16x8*)(lds + PG8_SB(b, h) + boff + n * 2048 + k * 1024); } while (0)
; #define PG8_MMA(ai, bj, At, Bt) do { __builtin_amdgcn_s_setprio(1); _Pragma("unroll") for (int m = 0; m < 4; ++m) _Pragma("unroll") for (int n = 0; n < 2; ++n) _Pragma("unroll") for (int k = 0; k < 2; ++k) \
;         acc[ai][bj][m][n] = __builtin_amdgcn_mfma_f32_16x16x32_bf16(Bt[n][k], At[m][k], acc[ai][bj][m][n], 0, 0, 0); __builtin_amdgcn_s_setprio(0); } while (0)
; #define PG8_WAIT_V(n) asm volatile("s_waitcnt vmcnt(" #n ")" ::: "memory")
; template <class Epi, class Sched>
; __device__ __forceinline__ void gemm_phase(LAS unsigned char* lds, const Gemm g, const Sched S, const Epi E, const int tid) {
;     ...
;             PG8_LDB(B0, 0, 0); PG8_LDB(B1, 0, 1); PG8_SCHED; PG8_LDA(At, 0, 0); PG8_STAGE(PG8_SA(1, 1), a1 + hstepA, voffA);
;             PG8_WAIT_V(8); PG8_WAIT_L(0); PG8_BAR; PG8_MMA(0, 0, At, B0); PG8_MMA(0, 1, At, B1); PG8_BAR; PG8_SCHED;
;             PG8_LDA(At, 0, 1); PG8_STAGE(PG8_SB(0, 0), b2, voffB); PG8_STAGE(PG8_SB(0, 1), b2 + hstepB, voffB); PG8_STAGE(PG8_SA(0, 0), a2, voffA);
;             PG8_WAIT_V(8); PG8_WAIT_L(0); PG8_BAR; PG8_MMA(1, 0, At, B0); PG8_MMA(1, 1, At, B1); PG8_BAR; PG8_SCHED;
;             PG8_LDB(B0, 1, 0); PG8_LDB(B1, 1, 1); PG8_SCHED; PG8_LDA(At, 1, 0); PG8_STAGE(PG8_SA(0, 1), a2 + hstepA, voffA);
;             PG8_WAIT_V(8); PG8_WAIT_L(0); PG8_BAR; PG8_MMA(0, 0, At, B0); PG8_MMA(0, 1, At, B1); PG8_BAR; PG8_SCHED;
;             PG8_LDA(At, 1, 1); PG8_STAGE(PG8_SB(1, 0), b3, voffB); PG8_STAGE(PG8_SB(1, 1), b3 + hstepB, voffB); PG8_STAGE(PG8_SA(1, 0), a3, voffA);
;             PG8_WAIT_V(8); PG8_WAIT_L(0); PG8_BAR; PG8_MMA(1, 0, At, B0); PG8_MMA(1, 1, At, B1); PG8_BAR; PG8_SCHED;
	s_setprio 1
	v_mfma_f32_16x16x32_bf16 v[50:53], v[10:13], v[84:87], v[50:53]
	v_mfma_f32_16x16x32_bf16 v[18:21], v[76:79], v[84:87], v[18:21]
	v_mfma_f32_16x16x32_bf16 v[22:25], v[10:13], v[96:99], v[22:25]
	v_mfma_f32_16x16x32_bf16 v[26:29], v[76:79], v[96:99], v[26:29]
	v_mfma_f32_16x16x32_bf16 v[30:33], v[10:13], v[104:107], v[30:33]
	v_mfma_f32_16x16x32_bf16 v[34:37], v[76:79], v[104:107], v[34:37]
	v_mfma_f32_16x16x32_bf16 v[38:41], v[10:13], v[112:115], v[38:41]
	v_mfma_f32_16x16x32_bf16 v[42:45], v[76:79], v[112:115], v[42:45]
	v_mfma_f32_16x16x32_bf16 v[50:53], v[14:17], v[92:95], v[50:53]
	v_mfma_f32_16x16x32_bf16 v[18:21], v[80:83], v[92:95], v[18:21]
	v_mfma_f32_16x16x32_bf16 v[22:25], v[14:17], v[100:103], v[22:25]
	v_mfma_f32_16x16x32_bf16 v[26:29], v[80:83], v[100:103], v[26:29]
	v_mfma_f32_16x16x32_bf16 v[30:33], v[14:17], v[108:111], v[30:33]
	v_mfma_f32_16x16x32_bf16 v[34:37], v[80:83], v[108:111], v[34:37]
	v_mfma_f32_16x16x32_bf16 v[38:41], v[14:17], v[116:119], v[38:41]
	v_mfma_f32_16x16x32_bf16 v[42:45], v[80:83], v[116:119], v[42:45]
	s_setprio 0
	s_barrier
	s_add_i32 vcc_lo, s45, s47
	s_mov_b64 s[6:7], 0x180
	s_add_i32 s95, vcc_lo, 0x2000
	v_lshl_add_u64 v[120:121], v[120:121], 0, s[6:7]
	s_mov_b32 m0, vcc_lo
	s_add_u32 s10, s42, 0x10180
	ds_read_b128 v[84:87], v71 offset:49152
	ds_read_b128 v[92:95], v71 offset:50176
	ds_read_b128 v[96:99], v71 offset:51200
	ds_read_b128 v[100:103], v71 offset:52224
	ds_read_b128 v[104:107], v71 offset:53248
	ds_read_b128 v[108:111], v71 offset:54272
	ds_read_b128 v[112:115], v71 offset:55296
	ds_read_b128 v[116:119], v71 offset:56320
	global_load_lds_dwordx4 v[120:121], off
	v_lshl_add_u64 v[120:121], v[122:123], 0, s[6:7]
	s_mov_b32 m0, s95
	s_addc_u32 s11, s43, 0
	global_load_lds_dwordx4 v[120:121], off
	v_lshl_add_u64 v[120:121], s[10:11], 0, v[68:69]
	s_mov_b32 m0, s85
	s_nop 0
	global_load_lds_dwordx4 v[120:121], off
	v_lshl_add_u64 v[120:121], s[10:11], 0, v[66:67]
	s_mov_b32 m0, s88
	s_nop 0
	global_load_lds_dwordx4 v[120:121], off
	v_lshl_add_u64 v[120:121], v[124:125], 0, s[6:7]
	s_mov_b32 m0, s83
	s_nop 0
	global_load_lds_dwordx4 v[120:121], off
	v_lshl_add_u64 v[120:121], v[126:127], 0, s[6:7]
	s_mov_b32 m0, s84
	s_nop 0
	global_load_lds_dwordx4 v[120:121], off
	s_waitcnt vmcnt(8) lgkmcnt(0)
	s_barrier
	s_setprio 1
	v_mfma_f32_16x16x32_bf16 v[46:49], v[76:79], v[84:87], v[46:49]
	v_mfma_f32_16x16x32_bf16 v[54:57], v[10:13], v[96:99], v[54:57]
	v_mfma_f32_16x16x32_bf16 v[58:61], v[76:79], v[96:99], v[58:61]
	v_mfma_f32_16x16x32_bf16 v[62:65], v[10:13], v[104:107], v[62:65]
	v_mfma_f32_16x16x32_bf16 v[2:5], v[10:13], v[112:115], v[2:5]
	v_mfma_f32_16x16x32_bf16 v[6:9], v[76:79], v[112:115], v[6:9]
	v_mfma_f32_16x16x32_bf16 v[88:91], v[10:13], v[84:87], v[88:91]
	v_mfma_f32_16x16x32_bf16 v[46:49], v[80:83], v[92:95], v[46:49]
	v_mfma_f32_16x16x32_bf16 v[54:57], v[14:17], v[100:103], v[54:57]
	v_mfma_f32_16x16x32_bf16 v[58:61], v[80:83], v[100:103], v[58:61]
	v_mfma_f32_16x16x32_bf16 v[62:65], v[14:17], v[108:111], v[62:65]
	v_mfma_f32_16x16x32_bf16 v[72:75], v[76:79], v[104:107], v[72:75]
	v_mfma_f32_16x16x32_bf16 v[2:5], v[14:17], v[116:119], v[2:5]
	v_mfma_f32_16x16x32_bf16 v[6:9], v[80:83], v[116:119], v[6:9]
	v_mfma_f32_16x16x32_bf16 v[88:91], v[14:17], v[92:95], v[88:91]
	v_mfma_f32_16x16x32_bf16 v[72:75], v[80:83], v[108:111], v[72:75]
	s_setprio 0
	s_barrier
	ds_read_b128 v[10:13], v130
	ds_read_b128 v[14:17], v130 offset:1024
	ds_read_b128 v[76:79], v130 offset:2048
	ds_read_b128 v[80:83], v130 offset:3072
	s_add_u32 s10, s40, 0x10180
	s_addc_u32 s11, s41, 0
	s_mov_b32 m0, s97
	v_lshl_add_u64 v[120:121], s[10:11], 0, v[68:69]
	ds_read_b128 v[84:87], v71
	ds_read_b128 v[92:95], v71 offset:1024
	ds_read_b128 v[96:99], v71 offset:2048
	ds_read_b128 v[100:103], v71 offset:3072
	ds_read_b128 v[104:107], v71 offset:4096
	ds_read_b128 v[108:111], v71 offset:5120
	ds_read_b128 v[112:115], v71 offset:6144
	ds_read_b128 v[116:119], v71 offset:7168
	global_load_lds_dwordx4 v[120:121], off
	v_lshl_add_u64 v[120:121], s[10:11], 0, v[66:67]
	s_mov_b32 m0, s13
	s_nop 0
	global_load_lds_dwordx4 v[120:121], off
	s_waitcnt vmcnt(8) lgkmcnt(0)
	s_barrier
	s_setprio 1
	v_mfma_f32_16x16x32_bf16 v[38:41], v[10:13], v[112:115], v[38:41]
	v_mfma_f32_16x16x32_bf16 v[50:53], v[10:13], v[84:87], v[50:53]
	v_mfma_f32_16x16x32_bf16 v[18:21], v[76:79], v[84:87], v[18:21]
	v_mfma_f32_16x16x32_bf16 v[22:25], v[10:13], v[96:99], v[22:25]
	v_mfma_f32_16x16x32_bf16 v[26:29], v[76:79], v[96:99], v[26:29]
	v_mfma_f32_16x16x32_bf16 v[30:33], v[10:13], v[104:107], v[30:33]
	v_mfma_f32_16x16x32_bf16 v[34:37], v[76:79], v[104:107], v[34:37]
	v_mfma_f32_16x16x32_bf16 v[84:87], v[14:17], v[116:119], v[38:41]
	v_mfma_f32_16x16x32_bf16 v[38:41], v[76:79], v[112:115], v[42:45]
	v_mfma_f32_16x16x32_bf16 v[50:53], v[14:17], v[92:95], v[50:53]
	v_mfma_f32_16x16x32_bf16 v[18:21], v[80:83], v[92:95], v[18:21]
	v_mfma_f32_16x16x32_bf16 v[22:25], v[14:17], v[100:103], v[22:25]
	v_mfma_f32_16x16x32_bf16 v[26:29], v[80:83], v[100:103], v[26:29]
	v_mfma_f32_16x16x32_bf16 v[30:33], v[14:17], v[108:111], v[30:33]
	v_mfma_f32_16x16x32_bf16 v[34:37], v[80:83], v[108:111], v[34:37]
	v_mfma_f32_16x16x32_bf16 v[42:45], v[80:83], v[116:119], v[38:41]
	s_setprio 0
	s_barrier
; #define PG8_STAGE(bufoff, gbase, voff) do { _Pragma("unroll") for (int _i = 0; _i < 2; ++_i) \
;         __builtin_amdgcn_global_load_lds((const unsigned*)((const char*)(gbase) + (voff)[_i]), (LAS unsigned*)(lds + (bufoff) + ldsw + _i * 8192), 16, 0, 0); } while (0)
; #define PG8_LDA(dst, b, h) do { _Pragma("unroll") for (int m = 0; m < 4; ++m) _Pragma("unroll") for (int k = 0; k < 2; ++k) dst[m][k] = *(const LAS bf16x8*)(lds + PG8_SA(b, h) + aoff + m * 2048 + k * 1024); } while (0)
; #define PG8_LDB(dst, b, h) do { _Pragma("unroll") for (int n = 0; n < 2; ++n) _Pragma("unroll") for (int k = 0; k < 2; ++k) dst[n][k] = *(const LAS bf16x8*)(lds + PG8_SB(b, h) + boff + n * 2048 + k * 1024); } while (0)
; #define PG8_MMA(ai, bj, At, Bt) do { __builtin_amdgcn_s_setprio(1); _Pragma("unroll") for (int m = 0; m < 4; ++m) _Pragma("unroll") for (int n = 0; n < 2; ++n) _Pragma("unroll") for (int k = 0; k < 2; ++k) \
;         acc[ai][bj][m][n] = __builtin_amdgcn_mfma_f32_16x16x32_bf16(Bt[n][k], At[m][k], acc[ai][bj][m][n], 0, 0, 0); __builtin_amdgcn_s_setprio(0); } while (0)
; #define PG8_WAIT_V(n) asm volatile("s_waitcnt vmcnt(" #n ")" ::: "memory")
; #define PG8_WAIT_L(n) asm volatile("s_waitcnt lgkmcnt(" #n ")" ::: "memory")
; #define PG8_BAR __builtin_amdgcn_s_barrier()
; #define PG8_SCHED __builtin_amdgcn_sched_barrier(0)
; template <class Epi, class Sched>
; __device__ __forceinline__ void gemm_phase(LAS unsigned char* lds, const Gemm g, const Sched S, const Epi E, const int tid) {
;     ...
;             PG8_LDA(At, 0, 1); PG8_STAGE(PG8_SB(0, 0), b2, voffB); PG8_STAGE(PG8_SB(0, 1), b2 + hstepB, voffB); PG8_STAGE(PG8_SA(0, 0), a2, voffA);
;             PG8_WAIT_V(8); PG8_WAIT_L(0); PG8_BAR; PG8_MMA(1, 0, At, B0); PG8_MMA(1, 1, At, B1); PG8_BAR; PG8_SCHED;
;             PG8_LDB(B0, 1, 0); PG8_LDB(B1, 1, 1); PG8_SCHED; PG8_LDA(At, 1, 0); PG8_STAGE(PG8_SA(0, 1), a2 + hstepA, voffA);
;             PG8_WAIT_V(8); PG8_WAIT_L(0); PG8_BAR; PG8_MMA(0, 0, At, B0); PG8_MMA(0, 1, At, B1); PG8_BAR; PG8_SCHED;
;             PG8_LDA(At, 1, 1); PG8_STAGE(PG8_SB(1, 0), b3, voffB); PG8_STAGE(PG8_SB(1, 1), b3 + hstepB, voffB); PG8_STAGE(PG8_SA(1, 0), a3, voffA);
;             PG8_WAIT_V(8); PG8_WAIT_L(0); PG8_BAR; PG8_MMA(1, 0, At, B0); PG8_MMA(1, 1, At, B1); PG8_BAR; PG8_SCHED;
;         }
;         if (wr == 0) PG8_BAR;
	s_mov_b32 m0, s96
	v_lshl_add_u64 v[132:133], s[26:27], 0, v[68:69]
	s_add_u32 s10, s26, 0x10000
	ds_read_b128 v[38:41], v71 offset:16384
	ds_read_b128 v[92:95], v71 offset:17408
	ds_read_b128 v[96:99], v71 offset:18432
	ds_read_b128 v[100:103], v71 offset:19456
	ds_read_b128 v[104:107], v71 offset:20480
	ds_read_b128 v[108:111], v71 offset:21504
	ds_read_b128 v[112:115], v71 offset:22528
	ds_read_b128 v[116:119], v71 offset:23552
	global_load_lds_dwordx4 v[132:133], off
	v_lshl_add_u64 v[134:135], s[26:27], 0, v[66:67]
	s_mov_b32 m0, s94
	s_addc_u32 s11, s27, 0
	global_load_lds_dwordx4 v[134:135], off
	v_lshl_add_u64 v[120:121], s[10:11], 0, v[68:69]
	s_mov_b32 m0, s48
	v_lshl_add_u64 v[136:137], s[28:29], 0, v[68:69]
	global_load_lds_dwordx4 v[120:121], off
	v_lshl_add_u64 v[120:121], s[10:11], 0, v[66:67]
	s_mov_b32 m0, s49
	v_lshl_add_u64 v[138:139], s[28:29], 0, v[66:67]
	global_load_lds_dwordx4 v[120:121], off
	s_mov_b32 m0, s37
	s_nop 0
	global_load_lds_dwordx4 v[136:137], off
	s_mov_b32 m0, s62
	s_nop 0
	global_load_lds_dwordx4 v[138:139], off
	s_waitcnt vmcnt(8) lgkmcnt(0)
	s_barrier
	s_setprio 1
	v_mfma_f32_16x16x32_bf16 v[88:91], v[10:13], v[38:41], v[88:91]
	v_mfma_f32_16x16x32_bf16 v[38:41], v[76:79], v[38:41], v[46:49]
	v_mfma_f32_16x16x32_bf16 v[88:91], v[14:17], v[92:95], v[88:91]
	v_mfma_f32_16x16x32_bf16 v[92:95], v[80:83], v[92:95], v[38:41]
	v_mfma_f32_16x16x32_bf16 v[38:41], v[10:13], v[96:99], v[54:57]
	v_mfma_f32_16x16x32_bf16 v[120:123], v[14:17], v[100:103], v[38:41]
	v_mfma_f32_16x16x32_bf16 v[38:41], v[76:79], v[96:99], v[58:61]
	v_mfma_f32_16x16x32_bf16 v[96:99], v[80:83], v[100:103], v[38:41]
	v_mfma_f32_16x16x32_bf16 v[38:41], v[10:13], v[104:107], v[62:65]
	v_mfma_f32_16x16x32_bf16 v[2:5], v[10:13], v[112:115], v[2:5]
	v_mfma_f32_16x16x32_bf16 v[100:103], v[14:17], v[108:111], v[38:41]
	v_mfma_f32_16x16x32_bf16 v[38:41], v[76:79], v[104:107], v[72:75]
	v_mfma_f32_16x16x32_bf16 v[2:5], v[14:17], v[116:119], v[2:5]
	v_mfma_f32_16x16x32_bf16 v[6:9], v[76:79], v[112:115], v[6:9]
	v_mfma_f32_16x16x32_bf16 v[72:75], v[80:83], v[108:111], v[38:41]
	v_mfma_f32_16x16x32_bf16 v[76:79], v[80:83], v[116:119], v[6:9]
	s_setprio 0
	s_barrier
	s_nop 1
	ds_read_b128 v[6:9], v131
	ds_read_b128 v[80:83], v131 offset:1024
	ds_read_b128 v[104:107], v131 offset:2048
	ds_read_b128 v[108:111], v131 offset:3072
	s_add_u32 s10, s28, 0x10000
	s_addc_u32 s11, s29, 0
	s_mov_b32 m0, s68
	v_lshl_add_u64 v[54:55], s[10:11], 0, v[68:69]
	ds_read_b128 v[10:13], v71 offset:32768
	ds_read_b128 v[14:17], v71 offset:33792
	ds_read_b128 v[38:41], v71 offset:34816
	ds_read_b128 v[46:49], v71 offset:35840
	ds_read_b128 v[112:115], v71 offset:36864
	ds_read_b128 v[116:119], v71 offset:37888
	ds_read_b128 v[124:127], v71 offset:38912
	ds_read_b128 v[128:131], v71 offset:39936
	global_load_lds_dwordx4 v[54:55], off
	v_lshl_add_u64 v[54:55], s[10:11], 0, v[66:67]
	s_mov_b32 m0, s69
	s_nop 0
	global_load_lds_dwordx4 v[54:55], off
	s_waitcnt vmcnt(8) lgkmcnt(0)
	s_barrier
	s_setprio 1
	v_mfma_f32_16x16x32_bf16 v[50:53], v[6:9], v[10:13], v[50:53]
	v_mfma_f32_16x16x32_bf16 v[10:13], v[104:107], v[10:13], v[18:21]
	v_mfma_f32_16x16x32_bf16 v[58:61], v[108:111], v[14:17], v[10:13]
	v_mfma_f32_16x16x32_bf16 v[10:13], v[6:9], v[38:41], v[22:25]
	v_mfma_f32_16x16x32_bf16 v[54:57], v[80:83], v[46:49], v[10:13]
	v_mfma_f32_16x16x32_bf16 v[10:13], v[104:107], v[38:41], v[26:29]
	v_mfma_f32_16x16x32_bf16 v[62:65], v[80:83], v[14:17], v[50:53]
	v_mfma_f32_16x16x32_bf16 v[50:53], v[108:111], v[46:49], v[10:13]
	v_mfma_f32_16x16x32_bf16 v[10:13], v[6:9], v[112:115], v[30:33]
	v_mfma_f32_16x16x32_bf16 v[46:49], v[80:83], v[116:119], v[10:13]
	v_mfma_f32_16x16x32_bf16 v[10:13], v[104:107], v[112:115], v[34:37]
	v_mfma_f32_16x16x32_bf16 v[38:41], v[108:111], v[116:119], v[10:13]
	v_mfma_f32_16x16x32_bf16 v[10:13], v[6:9], v[124:127], v[84:87]
	v_mfma_f32_16x16x32_bf16 v[30:33], v[80:83], v[128:131], v[10:13]
	v_mfma_f32_16x16x32_bf16 v[10:13], v[104:107], v[124:127], v[42:45]
	v_mfma_f32_16x16x32_bf16 v[22:25], v[108:111], v[128:131], v[10:13]
	s_setprio 0
	s_barrier
	s_mov_b32 m0, vcc_lo
	v_lshl_add_u64 v[26:27], v[132:133], 0, s[64:65]
	s_add_u32 s10, s26, 0x10080
	ds_read_b128 v[10:13], v71 offset:49152
	ds_read_b128 v[14:17], v71 offset:50176
	ds_read_b128 v[18:21], v71 offset:51200
	ds_read_b128 v[84:87], v71 offset:52224
	ds_read_b128 v[112:115], v71 offset:53248
	ds_read_b128 v[116:119], v71 offset:54272
	ds_read_b128 v[124:127], v71 offset:55296
	ds_read_b128 v[128:131], v71 offset:56320
	global_load_lds_dwordx4 v[26:27], off
	v_lshl_add_u64 v[26:27], v[134:135], 0, s[64:65]
	s_mov_b32 m0, s95
	s_addc_u32 s11, s27, 0
	global_load_lds_dwordx4 v[26:27], off
	v_lshl_add_u64 v[26:27], s[10:11], 0, v[68:69]
	s_mov_b32 m0, s85
	s_nop 0
	global_load_lds_dwordx4 v[26:27], off
	v_lshl_add_u64 v[26:27], s[10:11], 0, v[66:67]
	s_mov_b32 m0, s88
	s_nop 0
	global_load_lds_dwordx4 v[26:27], off
	v_lshl_add_u64 v[26:27], v[136:137], 0, s[64:65]
	s_mov_b32 m0, s83
	s_nop 0
	global_load_lds_dwordx4 v[26:27], off
	v_lshl_add_u64 v[26:27], v[138:139], 0, s[64:65]
	s_mov_b32 m0, s84
	s_nop 0
	global_load_lds_dwordx4 v[26:27], off
	s_waitcnt vmcnt(8) lgkmcnt(0)
	s_barrier
	s_setprio 1
	v_mfma_f32_16x16x32_bf16 v[26:29], v[6:9], v[10:13], v[88:91]
	v_mfma_f32_16x16x32_bf16 v[10:13], v[104:107], v[10:13], v[92:95]
	v_mfma_f32_16x16x32_bf16 v[34:37], v[108:111], v[14:17], v[10:13]
	v_mfma_f32_16x16x32_bf16 v[10:13], v[6:9], v[18:21], v[120:123]
	v_mfma_f32_16x16x32_bf16 v[42:45], v[80:83], v[14:17], v[26:29]
	v_mfma_f32_16x16x32_bf16 v[26:29], v[80:83], v[84:87], v[10:13]
	v_mfma_f32_16x16x32_bf16 v[10:13], v[104:107], v[18:21], v[96:99]
	v_mfma_f32_16x16x32_bf16 v[18:21], v[108:111], v[84:87], v[10:13]
	v_mfma_f32_16x16x32_bf16 v[10:13], v[6:9], v[112:115], v[100:103]
	v_mfma_f32_16x16x32_bf16 v[2:5], v[6:9], v[124:127], v[2:5]
	v_mfma_f32_16x16x32_bf16 v[14:17], v[80:83], v[116:119], v[10:13]
	v_mfma_f32_16x16x32_bf16 v[10:13], v[104:107], v[112:115], v[72:75]
	v_mfma_f32_16x16x32_bf16 v[6:9], v[80:83], v[128:131], v[2:5]
	v_mfma_f32_16x16x32_bf16 v[2:5], v[104:107], v[124:127], v[76:79]
	v_mfma_f32_16x16x32_bf16 v[10:13], v[108:111], v[116:119], v[10:13]
	v_mfma_f32_16x16x32_bf16 v[2:5], v[108:111], v[128:131], v[2:5]
	s_setprio 0
	s_barrier
	s_andn2_b64 vcc, exec, s[18:19]
	s_cbranch_vccnz .LBB0_312
	s_barrier

; #define PG8_STAGE(bufoff, gbase, voff) do { _Pragma("unroll") for (int _i = 0; _i < 2; ++_i) \
;         __builtin_amdgcn_global_load_lds((const unsigned*)((const char*)(gbase) + (voff)[_i]), (LAS unsigned*)(lds + (bufoff) + ldsw + _i * 8192), 16, 0, 0); } while (0)
; #define PG8_LDA(dst, b, h) do { _Pragma("unroll") for (int m = 0; m < 4; ++m) _Pragma("unroll") for (int k = 0; k < 2; ++k) dst[m][k] = *(const LAS bf16x8*)(lds + PG8_SA(b, h) + aoff + m * 2048 + k * 1024); } while (0)
; #define PG8_LDB(dst, b, h) do { _Pragma("unroll") for (int n = 0; n < 2; ++n) _Pragma("unroll") for (int k = 0; k < 2; ++k) dst[n][k] = *(const LAS bf16x8*)(lds + PG8_SB(b, h) + boff + n * 2048 + k * 1024); } while (0)
; #define PG8_MMA(ai, bj, At, Bt) do { __builtin_amdgcn_s_setprio(1); _Pragma("unroll") for (int m = 0; m < 4; ++m) _Pragma("unroll") for (int n = 0; n < 2; ++n) _Pragma("unroll") for (int k = 0; k < 2; ++k) \
;         acc[ai][bj][m][n] = __builtin_amdgcn_mfma_f32_16x16x32_bf16(Bt[n][k], At[m][k], acc[ai][bj][m][n], 0, 0, 0); __builtin_amdgcn_s_setprio(0); } while (0)
; #define PG8_WAIT_V(n) asm volatile("s_waitcnt vmcnt(" #n ")" ::: "memory")
; #define PG8_WAIT_L(n) asm volatile("s_waitcnt lgkmcnt(" #n ")" ::: "memory")
; #define PG8_BAR __builtin_amdgcn_s_barrier()
; #define PG8_SCHED __builtin_amdgcn_sched_barrier(0)
; template <class Epi, class Sched>
; __device__ __forceinline__ void gemm_phase(LAS unsigned char* lds, const Gemm g, const Sched S, const Epi E, const int tid) {
;     ...
;         for (int t = 0; t < nt; t += 2) {
;             const bool last = (t == nt - 2);
;             const char* a1 = cA + (size_t)(t + 1) * kstep;
;             const char* a2 = last ? nA : cA + (size_t)(t + 2) * kstep; const char* b2 = last ? nB : cB + (size_t)(t + 2) * kstep;
;             const char* a3 = a2 + kstep; const char* b3 = b2 + kstep;
;             PG8_LDB(B0, 0, 0); PG8_LDB(B1, 0, 1); PG8_SCHED; PG8_LDA(At, 0, 0); PG8_STAGE(PG8_SA(1, 1), a1 + hstepA, voffA);
;             PG8_WAIT_V(8); PG8_WAIT_L(0); PG8_BAR; PG8_MMA(0, 0, At, B0); PG8_MMA(0, 1, At, B1); PG8_BAR; PG8_SCHED;
;             PG8_LDA(At, 0, 1); PG8_STAGE(PG8_SB(0, 0), b2, voffB); PG8_STAGE(PG8_SB(0, 1), b2 + hstepB, voffB); PG8_STAGE(PG8_SA(0, 0), a2, voffA);
;             PG8_WAIT_V(8); PG8_WAIT_L(0); PG8_BAR; PG8_MMA(1, 0, At, B0); PG8_MMA(1, 1, At, B1); PG8_BAR; PG8_SCHED;
.LBB0_332:
	s_add_u32 s10, s44, 0xfffc0080
	s_addc_u32 s11, s45, -1
	s_add_i32 vcc_lo, 0, 0x10000
	s_cmp_eq_u32 s97, 12
	s_cselect_b32 s83, s7, s11
	s_cselect_b32 s82, s92, s10
	v_add_u32_e32 v154, vcc_lo, v157
	s_cselect_b32 s47, s93, s96
	s_cselect_b32 s46, s94, s95
	s_add_i32 vcc_hi, 0, 0x14000
	s_waitcnt lgkmcnt(0)
	ds_read_b128 v[130:133], v154
	ds_read_b128 v[134:137], v154 offset:1024
	ds_read_b128 v[150:153], v154 offset:2048
	ds_read_b128 v[160:163], v154 offset:3072
	v_add_u32_e32 v154, vcc_hi, v157
	ds_read_b128 v[164:167], v154
	ds_read_b128 v[180:183], v154 offset:1024
	ds_read_b128 v[184:187], v154 offset:2048
	ds_read_b128 v[188:191], v154 offset:3072
	v_lshl_add_u64 v[154:155], s[44:45], 0, v[148:149]
	s_add_i32 m0, s48, 0xc000
	ds_read_b128 v[192:195], v158
	ds_read_b128 v[196:199], v158 offset:1024
	ds_read_b128 v[200:203], v158 offset:2048
	ds_read_b128 v[204:207], v158 offset:3072
	ds_read_b128 v[208:211], v158 offset:4096
	ds_read_b128 v[212:215], v158 offset:5120
	ds_read_b128 v[216:219], v158 offset:6144
	ds_read_b128 v[220:223], v158 offset:7168
	global_load_lds_dwordx4 v[154:155], off
	v_lshl_add_u64 v[154:155], s[44:45], 0, v[146:147]
	s_add_i32 m0, s48, 0xe000
	s_nop 0
	global_load_lds_dwordx4 v[154:155], off
	s_waitcnt vmcnt(8) lgkmcnt(0)
	s_barrier
	s_setprio 1
	v_mfma_f32_16x16x32_bf16 v[122:125], v[130:133], v[192:195], v[122:125]
	v_mfma_f32_16x16x32_bf16 v[114:117], v[150:153], v[192:195], v[114:117]
	v_mfma_f32_16x16x32_bf16 v[106:109], v[130:133], v[200:203], v[106:109]
	v_mfma_f32_16x16x32_bf16 v[98:101], v[150:153], v[200:203], v[98:101]
	v_mfma_f32_16x16x32_bf16 v[90:93], v[130:133], v[208:211], v[90:93]
	v_mfma_f32_16x16x32_bf16 v[82:85], v[150:153], v[208:211], v[82:85]
	v_mfma_f32_16x16x32_bf16 v[74:77], v[130:133], v[216:219], v[74:77]
	v_mfma_f32_16x16x32_bf16 v[66:69], v[150:153], v[216:219], v[66:69]
	v_mfma_f32_16x16x32_bf16 v[122:125], v[134:137], v[196:199], v[122:125]
	v_mfma_f32_16x16x32_bf16 v[114:117], v[160:163], v[196:199], v[114:117]
	v_mfma_f32_16x16x32_bf16 v[106:109], v[134:137], v[204:207], v[106:109]
	v_mfma_f32_16x16x32_bf16 v[98:101], v[160:163], v[204:207], v[98:101]
	v_mfma_f32_16x16x32_bf16 v[90:93], v[134:137], v[212:215], v[90:93]
	v_mfma_f32_16x16x32_bf16 v[82:85], v[160:163], v[212:215], v[82:85]
	v_mfma_f32_16x16x32_bf16 v[74:77], v[134:137], v[220:223], v[74:77]
	v_mfma_f32_16x16x32_bf16 v[66:69], v[160:163], v[220:223], v[66:69]
	v_mfma_f32_16x16x32_bf16 v[126:129], v[164:167], v[192:195], v[126:129]
	v_mfma_f32_16x16x32_bf16 v[118:121], v[184:187], v[192:195], v[118:121]
	v_mfma_f32_16x16x32_bf16 v[110:113], v[164:167], v[200:203], v[110:113]
	v_mfma_f32_16x16x32_bf16 v[102:105], v[184:187], v[200:203], v[102:105]
	v_mfma_f32_16x16x32_bf16 v[94:97], v[164:167], v[208:211], v[94:97]
	v_mfma_f32_16x16x32_bf16 v[86:89], v[184:187], v[208:211], v[86:89]
	v_mfma_f32_16x16x32_bf16 v[78:81], v[164:167], v[216:219], v[78:81]
	v_mfma_f32_16x16x32_bf16 v[70:73], v[184:187], v[216:219], v[70:73]
	v_mfma_f32_16x16x32_bf16 v[126:129], v[180:183], v[196:199], v[126:129]
	v_mfma_f32_16x16x32_bf16 v[118:121], v[188:191], v[196:199], v[118:121]
	v_mfma_f32_16x16x32_bf16 v[110:113], v[180:183], v[204:207], v[110:113]
	v_mfma_f32_16x16x32_bf16 v[102:105], v[188:191], v[204:207], v[102:105]
	v_mfma_f32_16x16x32_bf16 v[94:97], v[180:183], v[212:215], v[94:97]
	v_mfma_f32_16x16x32_bf16 v[86:89], v[188:191], v[212:215], v[86:89]
	v_mfma_f32_16x16x32_bf16 v[78:81], v[180:183], v[220:223], v[78:81]
	v_mfma_f32_16x16x32_bf16 v[70:73], v[188:191], v[220:223], v[70:73]
	s_setprio 0
	s_barrier
	s_add_i32 s10, vcc_lo, s37
	v_lshl_add_u64 v[154:155], s[46:47], 0, v[140:141]
	s_mov_b32 m0, s10
	ds_read_b128 v[192:195], v158 offset:16384
	ds_read_b128 v[196:199], v158 offset:17408
	ds_read_b128 v[200:203], v158 offset:18432
	ds_read_b128 v[204:207], v158 offset:19456
	ds_read_b128 v[208:211], v158 offset:20480
	ds_read_b128 v[212:215], v158 offset:21504
	ds_read_b128 v[216:219], v158 offset:22528
	ds_read_b128 v[220:223], v158 offset:23552
	global_load_lds_dwordx4 v[154:155], off
	s_add_i32 m0, s10, 0x2000
	s_add_u32 s10, s46, 0x40000
	v_lshl_add_u64 v[224:225], s[46:47], 0, v[144:145]
	s_addc_u32 s11, s47, 0
	s_add_i32 vcc_lo, vcc_hi, s37
	global_load_lds_dwordx4 v[224:225], off
	v_lshl_add_u64 v[226:227], s[10:11], 0, v[140:141]
	s_mov_b32 m0, vcc_lo
	v_lshl_add_u64 v[228:229], s[82:83], 0, v[142:143]
	global_load_lds_dwordx4 v[226:227], off
	v_lshl_add_u64 v[226:227], s[10:11], 0, v[144:145]
	s_add_i32 m0, vcc_lo, 0x2000
	s_nop 0
	global_load_lds_dwordx4 v[226:227], off
	v_lshl_add_u64 v[226:227], s[82:83], 0, v[138:139]
	s_mov_b32 m0, s48
	s_nop 0
	global_load_lds_dwordx4 v[226:227], off
	s_mov_b32 m0, s49
	s_nop 0
	global_load_lds_dwordx4 v[228:229], off
	s_waitcnt vmcnt(8) lgkmcnt(0)
	s_barrier
; #define PG8_STAGE(bufoff, gbase, voff) do { _Pragma("unroll") for (int _i = 0; _i < 2; ++_i) \
;         __builtin_amdgcn_global_load_lds((const unsigned*)((const char*)(gbase) + (voff)[_i]), (LAS unsigned*)(lds + (bufoff) + ldsw + _i * 8192), 16, 0, 0); } while (0)
; #define PG8_LDA(dst, b, h) do { _Pragma("unroll") for (int m = 0; m < 4; ++m) _Pragma("unroll") for (int k = 0; k < 2; ++k) dst[m][k] = *(const LAS bf16x8*)(lds + PG8_SA(b, h) + aoff + m * 2048 + k * 1024); } while (0)
; #define PG8_LDB(dst, b, h) do { _Pragma("unroll") for (int n = 0; n < 2; ++n) _Pragma("unroll") for (int k = 0; k < 2; ++k) dst[n][k] = *(const LAS bf16x8*)(lds + PG8_SB(b, h) + boff + n * 2048 + k * 1024); } while (0)
; #define PG8_MMA(ai, bj, At, Bt) do { __builtin_amdgcn_s_setprio(1); _Pragma("unroll") for (int m = 0; m < 4; ++m) _Pragma("unroll") for (int n = 0; n < 2; ++n) _Pragma("unroll") for (int k = 0; k < 2; ++k) \
;         acc[ai][bj][m][n] = __builtin_amdgcn_mfma_f32_16x16x32_bf16(Bt[n][k], At[m][k], acc[ai][bj][m][n], 0, 0, 0); __builtin_amdgcn_s_setprio(0); } while (0)
; #define PG8_WAIT_V(n) asm volatile("s_waitcnt vmcnt(" #n ")" ::: "memory")
; #define PG8_WAIT_L(n) asm volatile("s_waitcnt lgkmcnt(" #n ")" ::: "memory")
; #define PG8_BAR __builtin_amdgcn_s_barrier()
; #define PG8_SCHED __builtin_amdgcn_sched_barrier(0)
; template <class Epi, class Sched>
; __device__ __forceinline__ void gemm_phase(LAS unsigned char* lds, const Gemm g, const Sched S, const Epi E, const int tid) {
;     ...
;             PG8_WAIT_V(8); PG8_WAIT_L(0); PG8_BAR; PG8_MMA(1, 0, At, B0); PG8_MMA(1, 1, At, B1); PG8_BAR; PG8_SCHED;
;             PG8_LDB(B0, 1, 0); PG8_LDB(B1, 1, 1); PG8_SCHED; PG8_LDA(At, 1, 0); PG8_STAGE(PG8_SA(0, 1), a2 + hstepA, voffA);
;             PG8_WAIT_V(8); PG8_WAIT_L(0); PG8_BAR; PG8_MMA(0, 0, At, B0); PG8_MMA(0, 1, At, B1); PG8_BAR; PG8_SCHED;
	s_setprio 1
	v_mfma_f32_16x16x32_bf16 v[58:61], v[130:133], v[192:195], v[58:61]
	v_mfma_f32_16x16x32_bf16 v[50:53], v[150:153], v[192:195], v[50:53]
	v_mfma_f32_16x16x32_bf16 v[42:45], v[130:133], v[200:203], v[42:45]
	v_mfma_f32_16x16x32_bf16 v[34:37], v[150:153], v[200:203], v[34:37]
	v_mfma_f32_16x16x32_bf16 v[26:29], v[130:133], v[208:211], v[26:29]
	v_mfma_f32_16x16x32_bf16 v[18:21], v[150:153], v[208:211], v[18:21]
	v_mfma_f32_16x16x32_bf16 v[10:13], v[130:133], v[216:219], v[10:13]
	v_mfma_f32_16x16x32_bf16 v[6:9], v[150:153], v[216:219], v[6:9]
	v_mfma_f32_16x16x32_bf16 v[58:61], v[134:137], v[196:199], v[58:61]
	v_mfma_f32_16x16x32_bf16 v[50:53], v[160:163], v[196:199], v[50:53]
	v_mfma_f32_16x16x32_bf16 v[42:45], v[134:137], v[204:207], v[42:45]
	v_mfma_f32_16x16x32_bf16 v[34:37], v[160:163], v[204:207], v[34:37]
	v_mfma_f32_16x16x32_bf16 v[26:29], v[134:137], v[212:215], v[26:29]
	v_mfma_f32_16x16x32_bf16 v[18:21], v[160:163], v[212:215], v[18:21]
	v_mfma_f32_16x16x32_bf16 v[10:13], v[134:137], v[220:223], v[10:13]
	v_mfma_f32_16x16x32_bf16 v[6:9], v[160:163], v[220:223], v[6:9]
	v_mfma_f32_16x16x32_bf16 v[62:65], v[164:167], v[192:195], v[62:65]
	v_mfma_f32_16x16x32_bf16 v[54:57], v[184:187], v[192:195], v[54:57]
	v_mfma_f32_16x16x32_bf16 v[46:49], v[164:167], v[200:203], v[46:49]
	v_mfma_f32_16x16x32_bf16 v[38:41], v[184:187], v[200:203], v[38:41]
	v_mfma_f32_16x16x32_bf16 v[30:33], v[164:167], v[208:211], v[30:33]
	v_mfma_f32_16x16x32_bf16 v[22:25], v[184:187], v[208:211], v[22:25]
	v_mfma_f32_16x16x32_bf16 v[14:17], v[164:167], v[216:219], v[14:17]
	v_mfma_f32_16x16x32_bf16 v[2:5], v[184:187], v[216:219], v[2:5]
	v_mfma_f32_16x16x32_bf16 v[62:65], v[180:183], v[196:199], v[62:65]
	v_mfma_f32_16x16x32_bf16 v[54:57], v[188:191], v[196:199], v[54:57]
	v_mfma_f32_16x16x32_bf16 v[46:49], v[180:183], v[204:207], v[46:49]
	v_mfma_f32_16x16x32_bf16 v[38:41], v[188:191], v[204:207], v[38:41]
	v_mfma_f32_16x16x32_bf16 v[30:33], v[180:183], v[212:215], v[30:33]
	v_mfma_f32_16x16x32_bf16 v[22:25], v[188:191], v[212:215], v[22:25]
	v_mfma_f32_16x16x32_bf16 v[14:17], v[180:183], v[220:223], v[14:17]
	v_mfma_f32_16x16x32_bf16 v[2:5], v[188:191], v[220:223], v[2:5]
	s_setprio 0
	s_barrier
	s_add_i32 vcc_lo, 0, 0x18000
	v_add_u32_e32 v159, vcc_lo, v157
	s_add_i32 vcc_hi, 0, 0x1c000
	ds_read_b128 v[130:133], v159
	ds_read_b128 v[134:137], v159 offset:1024
	ds_read_b128 v[150:153], v159 offset:2048
	ds_read_b128 v[160:163], v159 offset:3072
	v_add_u32_e32 v159, vcc_hi, v157
	ds_read_b128 v[164:167], v159
	ds_read_b128 v[180:183], v159 offset:1024
	ds_read_b128 v[184:187], v159 offset:2048
	ds_read_b128 v[188:191], v159 offset:3072
	s_add_u32 s10, s82, 0x40000
	s_addc_u32 s11, s83, 0
	s_mov_b32 m0, s62
	v_lshl_add_u64 v[230:231], s[10:11], 0, v[138:139]
	ds_read_b128 v[192:195], v158 offset:32768
	ds_read_b128 v[196:199], v158 offset:33792
	ds_read_b128 v[200:203], v158 offset:34816
	ds_read_b128 v[204:207], v158 offset:35840
	ds_read_b128 v[208:211], v158 offset:36864
	ds_read_b128 v[212:215], v158 offset:37888
	ds_read_b128 v[216:219], v158 offset:38912
	ds_read_b128 v[220:223], v158 offset:39936
	global_load_lds_dwordx4 v[230:231], off
	v_lshl_add_u64 v[230:231], s[10:11], 0, v[142:143]
	s_mov_b32 m0, s68
	s_nop 0
	global_load_lds_dwordx4 v[230:231], off
	s_waitcnt vmcnt(8) lgkmcnt(0)
	s_barrier
	s_setprio 1
	v_mfma_f32_16x16x32_bf16 v[122:125], v[130:133], v[192:195], v[122:125]
	v_mfma_f32_16x16x32_bf16 v[114:117], v[150:153], v[192:195], v[114:117]
	v_mfma_f32_16x16x32_bf16 v[106:109], v[130:133], v[200:203], v[106:109]
	v_mfma_f32_16x16x32_bf16 v[98:101], v[150:153], v[200:203], v[98:101]
	v_mfma_f32_16x16x32_bf16 v[90:93], v[130:133], v[208:211], v[90:93]
	v_mfma_f32_16x16x32_bf16 v[82:85], v[150:153], v[208:211], v[82:85]
	v_mfma_f32_16x16x32_bf16 v[74:77], v[130:133], v[216:219], v[74:77]
	v_mfma_f32_16x16x32_bf16 v[66:69], v[150:153], v[216:219], v[66:69]
	v_mfma_f32_16x16x32_bf16 v[122:125], v[134:137], v[196:199], v[122:125]
	v_mfma_f32_16x16x32_bf16 v[114:117], v[160:163], v[196:199], v[114:117]
	v_mfma_f32_16x16x32_bf16 v[106:109], v[134:137], v[204:207], v[106:109]
	v_mfma_f32_16x16x32_bf16 v[98:101], v[160:163], v[204:207], v[98:101]
	v_mfma_f32_16x16x32_bf16 v[90:93], v[134:137], v[212:215], v[90:93]
	v_mfma_f32_16x16x32_bf16 v[82:85], v[160:163], v[212:215], v[82:85]
	v_mfma_f32_16x16x32_bf16 v[74:77], v[134:137], v[220:223], v[74:77]
	v_mfma_f32_16x16x32_bf16 v[66:69], v[160:163], v[220:223], v[66:69]
	v_mfma_f32_16x16x32_bf16 v[126:129], v[164:167], v[192:195], v[126:129]
	v_mfma_f32_16x16x32_bf16 v[118:121], v[184:187], v[192:195], v[118:121]
	v_mfma_f32_16x16x32_bf16 v[110:113], v[164:167], v[200:203], v[110:113]
	v_mfma_f32_16x16x32_bf16 v[102:105], v[184:187], v[200:203], v[102:105]
	v_mfma_f32_16x16x32_bf16 v[94:97], v[164:167], v[208:211], v[94:97]
	v_mfma_f32_16x16x32_bf16 v[86:89], v[184:187], v[208:211], v[86:89]
	v_mfma_f32_16x16x32_bf16 v[78:81], v[164:167], v[216:219], v[78:81]
	v_mfma_f32_16x16x32_bf16 v[70:73], v[184:187], v[216:219], v[70:73]
	v_mfma_f32_16x16x32_bf16 v[126:129], v[180:183], v[196:199], v[126:129]
	v_mfma_f32_16x16x32_bf16 v[118:121], v[188:191], v[196:199], v[118:121]
	v_mfma_f32_16x16x32_bf16 v[110:113], v[180:183], v[204:207], v[110:113]
	v_mfma_f32_16x16x32_bf16 v[102:105], v[188:191], v[204:207], v[102:105]
	v_mfma_f32_16x16x32_bf16 v[94:97], v[180:183], v[212:215], v[94:97]
	v_mfma_f32_16x16x32_bf16 v[86:89], v[188:191], v[212:215], v[86:89]
	v_mfma_f32_16x16x32_bf16 v[78:81], v[180:183], v[220:223], v[78:81]
	v_mfma_f32_16x16x32_bf16 v[70:73], v[188:191], v[220:223], v[70:73]
	s_setprio 0
	s_barrier
; #define PG8_STAGE(bufoff, gbase, voff) do { _Pragma("unroll") for (int _i = 0; _i < 2; ++_i) \
;         __builtin_amdgcn_global_load_lds((const unsigned*)((const char*)(gbase) + (voff)[_i]), (LAS unsigned*)(lds + (bufoff) + ldsw + _i * 8192), 16, 0, 0); } while (0)
; #define PG8_LDA(dst, b, h) do { _Pragma("unroll") for (int m = 0; m < 4; ++m) _Pragma("unroll") for (int k = 0; k < 2; ++k) dst[m][k] = *(const LAS bf16x8*)(lds + PG8_SA(b, h) + aoff + m * 2048 + k * 1024); } while (0)
; #define PG8_MMA(ai, bj, At, Bt) do { __builtin_amdgcn_s_setprio(1); _Pragma("unroll") for (int m = 0; m < 4; ++m) _Pragma("unroll") for (int n = 0; n < 2; ++n) _Pragma("unroll") for (int k = 0; k < 2; ++k) \
;         acc[ai][bj][m][n] = __builtin_amdgcn_mfma_f32_16x16x32_bf16(Bt[n][k], At[m][k], acc[ai][bj][m][n], 0, 0, 0); __builtin_amdgcn_s_setprio(0); } while (0)
; #define PG8_WAIT_V(n) asm volatile("s_waitcnt vmcnt(" #n ")" ::: "memory")
; #define PG8_WAIT_L(n) asm volatile("s_waitcnt lgkmcnt(" #n ")" ::: "memory")
; #define PG8_BAR __builtin_amdgcn_s_barrier()
; #define PG8_SCHED __builtin_amdgcn_sched_barrier(0)
; template <class Epi, class Sched>
; __device__ __forceinline__ void gemm_phase(LAS unsigned char* lds, const Gemm g, const Sched S, const Epi E, const int tid) {
;     ...
;             PG8_LDA(At, 1, 1); PG8_STAGE(PG8_SB(1, 0), b3, voffB); PG8_STAGE(PG8_SB(1, 1), b3 + hstepB, voffB); PG8_STAGE(PG8_SA(1, 0), a3, voffA);
;             PG8_WAIT_V(8); PG8_WAIT_L(0); PG8_BAR; PG8_MMA(1, 0, At, B0); PG8_MMA(1, 1, At, B1); PG8_BAR; PG8_SCHED;
;         }
	s_add_i32 s10, vcc_lo, s37
	v_lshl_add_u64 v[154:155], v[154:155], 0, s[64:65]
	s_mov_b32 m0, s10
	ds_read_b128 v[192:195], v158 offset:49152
	ds_read_b128 v[196:199], v158 offset:50176
	ds_read_b128 v[200:203], v158 offset:51200
	ds_read_b128 v[204:207], v158 offset:52224
	ds_read_b128 v[208:211], v158 offset:53248
	ds_read_b128 v[212:215], v158 offset:54272
	ds_read_b128 v[216:219], v158 offset:55296
	ds_read_b128 v[220:223], v158 offset:56320
	global_load_lds_dwordx4 v[154:155], off
	s_add_i32 m0, s10, 0x2000
	s_add_u32 s10, s46, 0x40080
	v_lshl_add_u64 v[154:155], v[224:225], 0, s[64:65]
	s_addc_u32 s11, s47, 0
	s_add_i32 s46, vcc_hi, s37
	global_load_lds_dwordx4 v[154:155], off
	v_lshl_add_u64 v[154:155], s[10:11], 0, v[140:141]
	s_mov_b32 m0, s46
	s_nop 0
	global_load_lds_dwordx4 v[154:155], off
	v_lshl_add_u64 v[154:155], s[10:11], 0, v[144:145]
	s_add_i32 m0, s46, 0x2000
	s_nop 0
	global_load_lds_dwordx4 v[154:155], off
	v_lshl_add_u64 v[154:155], v[226:227], 0, s[64:65]
	s_mov_b32 m0, s88
	s_nop 0
	global_load_lds_dwordx4 v[154:155], off
	v_lshl_add_u64 v[154:155], v[228:229], 0, s[64:65]
	s_mov_b32 m0, s89
	s_nop 0
	global_load_lds_dwordx4 v[154:155], off
	s_waitcnt vmcnt(8) lgkmcnt(0)
	s_barrier
	s_setprio 1
	v_mfma_f32_16x16x32_bf16 v[58:61], v[130:133], v[192:195], v[58:61]
	v_mfma_f32_16x16x32_bf16 v[50:53], v[150:153], v[192:195], v[50:53]
	v_mfma_f32_16x16x32_bf16 v[42:45], v[130:133], v[200:203], v[42:45]
	v_mfma_f32_16x16x32_bf16 v[34:37], v[150:153], v[200:203], v[34:37]
	v_mfma_f32_16x16x32_bf16 v[26:29], v[130:133], v[208:211], v[26:29]
	v_mfma_f32_16x16x32_bf16 v[18:21], v[150:153], v[208:211], v[18:21]
	v_mfma_f32_16x16x32_bf16 v[10:13], v[130:133], v[216:219], v[10:13]
	v_mfma_f32_16x16x32_bf16 v[6:9], v[150:153], v[216:219], v[6:9]
	v_mfma_f32_16x16x32_bf16 v[58:61], v[134:137], v[196:199], v[58:61]
	v_mfma_f32_16x16x32_bf16 v[50:53], v[160:163], v[196:199], v[50:53]
	v_mfma_f32_16x16x32_bf16 v[42:45], v[134:137], v[204:207], v[42:45]
	v_mfma_f32_16x16x32_bf16 v[34:37], v[160:163], v[204:207], v[34:37]
	v_mfma_f32_16x16x32_bf16 v[26:29], v[134:137], v[212:215], v[26:29]
	v_mfma_f32_16x16x32_bf16 v[18:21], v[160:163], v[212:215], v[18:21]
	v_mfma_f32_16x16x32_bf16 v[10:13], v[134:137], v[220:223], v[10:13]
	v_mfma_f32_16x16x32_bf16 v[6:9], v[160:163], v[220:223], v[6:9]
	v_mfma_f32_16x16x32_bf16 v[62:65], v[164:167], v[192:195], v[62:65]
	v_mfma_f32_16x16x32_bf16 v[54:57], v[184:187], v[192:195], v[54:57]
	v_mfma_f32_16x16x32_bf16 v[46:49], v[164:167], v[200:203], v[46:49]
	v_mfma_f32_16x16x32_bf16 v[38:41], v[184:187], v[200:203], v[38:41]
	v_mfma_f32_16x16x32_bf16 v[30:33], v[164:167], v[208:211], v[30:33]
	v_mfma_f32_16x16x32_bf16 v[22:25], v[184:187], v[208:211], v[22:25]
	v_mfma_f32_16x16x32_bf16 v[14:17], v[164:167], v[216:219], v[14:17]
	v_mfma_f32_16x16x32_bf16 v[2:5], v[184:187], v[216:219], v[2:5]
	v_mfma_f32_16x16x32_bf16 v[62:65], v[180:183], v[196:199], v[62:65]
	v_mfma_f32_16x16x32_bf16 v[54:57], v[188:191], v[196:199], v[54:57]
	v_mfma_f32_16x16x32_bf16 v[46:49], v[180:183], v[204:207], v[46:49]
	v_mfma_f32_16x16x32_bf16 v[38:41], v[188:191], v[204:207], v[38:41]
	v_mfma_f32_16x16x32_bf16 v[30:33], v[180:183], v[212:215], v[30:33]
	v_mfma_f32_16x16x32_bf16 v[22:25], v[188:191], v[212:215], v[22:25]
	v_mfma_f32_16x16x32_bf16 v[14:17], v[180:183], v[220:223], v[14:17]
	v_mfma_f32_16x16x32_bf16 v[2:5], v[188:191], v[220:223], v[2:5]
	s_setprio 0
	s_barrier
	s_add_i32 s97, s97, 2
	s_add_u32 s95, s95, 0x100
	s_addc_u32 s96, s96, 0
	s_add_u32 s44, s44, 0x100
	s_addc_u32 s45, s45, 0
	s_cmp_gt_u32 s97, 13
	s_cbranch_scc0 .LBB0_332
	s_and_b64 vcc, exec, s[14:15]
	s_cbranch_vccz .LBB0_335
	s_barrier

; #define PG8_STAGE(bufoff, gbase, voff) do { _Pragma("unroll") for (int _i = 0; _i < 2; ++_i) \
;         __builtin_amdgcn_global_load_lds((const unsigned*)((const char*)(gbase) + (voff)[_i]), (LAS unsigned*)(lds + (bufoff) + ldsw + _i * 8192), 16, 0, 0); } while (0)
; #define PG8_LDA(dst, b, h) do { _Pragma("unroll") for (int m = 0; m < 4; ++m) _Pragma("unroll") for (int k = 0; k < 2; ++k) dst[m][k] = *(const LAS bf16x8*)(lds + PG8_SA(b, h) + aoff + m * 2048 + k * 1024); } while (0)
; #define PG8_LDB(dst, b, h) do { _Pragma("unroll") for (int n = 0; n < 2; ++n) _Pragma("unroll") for (int k = 0; k < 2; ++k) dst[n][k] = *(const LAS bf16x8*)(lds + PG8_SB(b, h) + boff + n * 2048 + k * 1024); } while (0)
; #define PG8_MMA(ai, bj, At, Bt) do { __builtin_amdgcn_s_setprio(1); _Pragma("unroll") for (int m = 0; m < 4; ++m) _Pragma("unroll") for (int n = 0; n < 2; ++n) _Pragma("unroll") for (int k = 0; k < 2; ++k) \
;         acc[ai][bj][m][n] = __builtin_amdgcn_mfma_f32_16x16x32_bf16(Bt[n][k], At[m][k], acc[ai][bj][m][n], 0, 0, 0); __builtin_amdgcn_s_setprio(0); } while (0)
; #define PG8_WAIT_V(n) asm volatile("s_waitcnt vmcnt(" #n ")" ::: "memory")
; #define PG8_WAIT_L(n) asm volatile("s_waitcnt lgkmcnt(" #n ")" ::: "memory")
; #define PG8_BAR __builtin_amdgcn_s_barrier()
; #define PG8_SCHED __builtin_amdgcn_sched_barrier(0)
; template <class Epi, class Sched>
; __device__ __forceinline__ void gemm_phase(LAS unsigned char* lds, const Gemm g, const Sched S, const Epi E, const int tid) {
;     ...
;         for (int t = 0; t < nt; t += 2) {
;             const bool last = (t == nt - 2);
;             const char* a1 = cA + (size_t)(t + 1) * kstep;
;             const char* a2 = last ? nA : cA + (size_t)(t + 2) * kstep; const char* b2 = last ? nB : cB + (size_t)(t + 2) * kstep;
;             const char* a3 = a2 + kstep; const char* b3 = b2 + kstep;
;             PG8_LDB(B0, 0, 0); PG8_LDB(B1, 0, 1); PG8_SCHED; PG8_LDA(At, 0, 0); PG8_STAGE(PG8_SA(1, 1), a1 + hstepA, voffA);
;             PG8_WAIT_V(8); PG8_WAIT_L(0); PG8_BAR; PG8_MMA(0, 0, At, B0); PG8_MMA(0, 1, At, B1); PG8_BAR; PG8_SCHED;
;             PG8_LDA(At, 0, 1); PG8_STAGE(PG8_SB(0, 0), b2, voffB); PG8_STAGE(PG8_SB(0, 1), b2 + hstepB, voffB); PG8_STAGE(PG8_SA(0, 0), a2, voffA);
;             PG8_WAIT_V(8); PG8_WAIT_L(0); PG8_BAR; PG8_MMA(1, 0, At, B0); PG8_MMA(1, 1, At, B1); PG8_BAR; PG8_SCHED;
.LBB0_471:
	s_add_u32 s12, s10, 0xfffc0080
	s_addc_u32 s13, s11, -1
	s_add_i32 s83, 0, 0x10000
	s_cmp_eq_u32 s82, 12
	s_cselect_b32 s15, s9, s13
	s_cselect_b32 s14, s45, s12
	s_cselect_b32 s13, s43, s62
	s_cselect_b32 s12, s48, s49
	s_add_i32 vcc_lo, 0, 0x14000
	v_add_u32_e32 v154, s83, v165
	v_add_u32_e32 v162, vcc_lo, v165
	ds_read_b128 v[50:53], v154
	ds_read_b128 v[102:105], v154 offset:1024
	ds_read_b128 v[150:153], v154 offset:2048
	ds_read_b128 v[154:157], v154 offset:3072
	ds_read_b128 v[158:161], v162
	ds_read_b128 v[180:183], v162 offset:1024
	ds_read_b128 v[184:187], v162 offset:2048
	ds_read_b128 v[188:191], v162 offset:3072
	v_lshl_add_u64 v[162:163], s[10:11], 0, v[148:149]
	s_add_i32 m0, s41, 0xc000
	ds_read_b128 v[192:195], v166
	ds_read_b128 v[196:199], v166 offset:1024
	ds_read_b128 v[200:203], v166 offset:2048
	ds_read_b128 v[204:207], v166 offset:3072
	ds_read_b128 v[208:211], v166 offset:4096
	ds_read_b128 v[212:215], v166 offset:5120
	ds_read_b128 v[216:219], v166 offset:6144
	ds_read_b128 v[220:223], v166 offset:7168
	global_load_lds_dwordx4 v[162:163], off
	v_lshl_add_u64 v[162:163], s[10:11], 0, v[146:147]
	s_add_i32 m0, s41, 0xe000
	s_nop 0
	global_load_lds_dwordx4 v[162:163], off
	s_waitcnt vmcnt(8) lgkmcnt(0)
	s_barrier
	s_setprio 1
	v_mfma_f32_16x16x32_bf16 v[130:133], v[50:53], v[192:195], v[130:133]
	v_mfma_f32_16x16x32_bf16 v[126:129], v[150:153], v[192:195], v[126:129]
	v_mfma_f32_16x16x32_bf16 v[114:117], v[50:53], v[200:203], v[114:117]
	v_mfma_f32_16x16x32_bf16 v[110:113], v[150:153], v[200:203], v[110:113]
	v_mfma_f32_16x16x32_bf16 v[94:97], v[50:53], v[208:211], v[94:97]
	v_mfma_f32_16x16x32_bf16 v[90:93], v[150:153], v[208:211], v[90:93]
	v_mfma_f32_16x16x32_bf16 v[78:81], v[50:53], v[216:219], v[78:81]
	v_mfma_f32_16x16x32_bf16 v[74:77], v[150:153], v[216:219], v[74:77]
	v_mfma_f32_16x16x32_bf16 v[130:133], v[102:105], v[196:199], v[130:133]
	v_mfma_f32_16x16x32_bf16 v[126:129], v[154:157], v[196:199], v[126:129]
	v_mfma_f32_16x16x32_bf16 v[114:117], v[102:105], v[204:207], v[114:117]
	v_mfma_f32_16x16x32_bf16 v[110:113], v[154:157], v[204:207], v[110:113]
	v_mfma_f32_16x16x32_bf16 v[94:97], v[102:105], v[212:215], v[94:97]
	v_mfma_f32_16x16x32_bf16 v[90:93], v[154:157], v[212:215], v[90:93]
	v_mfma_f32_16x16x32_bf16 v[78:81], v[102:105], v[220:223], v[78:81]
	v_mfma_f32_16x16x32_bf16 v[74:77], v[154:157], v[220:223], v[74:77]
	v_mfma_f32_16x16x32_bf16 v[134:137], v[158:161], v[192:195], v[134:137]
	v_mfma_f32_16x16x32_bf16 v[122:125], v[184:187], v[192:195], v[122:125]
	v_mfma_f32_16x16x32_bf16 v[118:121], v[158:161], v[200:203], v[118:121]
	v_mfma_f32_16x16x32_bf16 v[106:109], v[184:187], v[200:203], v[106:109]
	v_mfma_f32_16x16x32_bf16 v[98:101], v[158:161], v[208:211], v[98:101]
	v_mfma_f32_16x16x32_bf16 v[86:89], v[184:187], v[208:211], v[86:89]
	v_mfma_f32_16x16x32_bf16 v[82:85], v[158:161], v[216:219], v[82:85]
	v_mfma_f32_16x16x32_bf16 v[70:73], v[184:187], v[216:219], v[70:73]
	v_mfma_f32_16x16x32_bf16 v[134:137], v[180:183], v[196:199], v[134:137]
	v_mfma_f32_16x16x32_bf16 v[122:125], v[188:191], v[196:199], v[122:125]
	v_mfma_f32_16x16x32_bf16 v[118:121], v[180:183], v[204:207], v[118:121]
	v_mfma_f32_16x16x32_bf16 v[106:109], v[188:191], v[204:207], v[106:109]
	v_mfma_f32_16x16x32_bf16 v[98:101], v[180:183], v[212:215], v[98:101]
	v_mfma_f32_16x16x32_bf16 v[86:89], v[188:191], v[212:215], v[86:89]
	v_mfma_f32_16x16x32_bf16 v[82:85], v[180:183], v[220:223], v[82:85]
	v_mfma_f32_16x16x32_bf16 v[70:73], v[188:191], v[220:223], v[70:73]
	s_setprio 0
	s_barrier
	s_add_i32 s83, s83, s37
	v_lshl_add_u64 v[162:163], s[12:13], 0, v[140:141]
	s_mov_b32 m0, s83
	ds_read_b128 v[192:195], v166 offset:16384
	ds_read_b128 v[196:199], v166 offset:17408
	ds_read_b128 v[200:203], v166 offset:18432
	ds_read_b128 v[204:207], v166 offset:19456
	ds_read_b128 v[208:211], v166 offset:20480
	ds_read_b128 v[212:215], v166 offset:21504
	ds_read_b128 v[216:219], v166 offset:22528
	ds_read_b128 v[220:223], v166 offset:23552
	global_load_lds_dwordx4 v[162:163], off
	s_add_i32 m0, s83, 0x2000
	s_add_u32 s84, s12, 0x40000
	v_lshl_add_u64 v[224:225], s[12:13], 0, v[144:145]
	s_addc_u32 s85, s13, 0
	s_add_i32 s83, vcc_lo, s37
	global_load_lds_dwordx4 v[224:225], off
	v_lshl_add_u64 v[226:227], s[84:85], 0, v[140:141]
	s_mov_b32 m0, s83
	v_lshl_add_u64 v[228:229], s[14:15], 0, v[142:143]
	global_load_lds_dwordx4 v[226:227], off
	v_lshl_add_u64 v[226:227], s[84:85], 0, v[144:145]
	s_add_i32 m0, s83, 0x2000
	s_nop 0
	global_load_lds_dwordx4 v[226:227], off
	v_lshl_add_u64 v[226:227], s[14:15], 0, v[138:139]
	s_mov_b32 m0, s41
	s_nop 0
	global_load_lds_dwordx4 v[226:227], off
	s_mov_b32 m0, s90
	s_nop 0
	global_load_lds_dwordx4 v[228:229], off
	s_waitcnt vmcnt(8) lgkmcnt(0)
	s_barrier
; #define PG8_STAGE(bufoff, gbase, voff) do { _Pragma("unroll") for (int _i = 0; _i < 2; ++_i) \
;         __builtin_amdgcn_global_load_lds((const unsigned*)((const char*)(gbase) + (voff)[_i]), (LAS unsigned*)(lds + (bufoff) + ldsw + _i * 8192), 16, 0, 0); } while (0)
; #define PG8_LDA(dst, b, h) do { _Pragma("unroll") for (int m = 0; m < 4; ++m) _Pragma("unroll") for (int k = 0; k < 2; ++k) dst[m][k] = *(const LAS bf16x8*)(lds + PG8_SA(b, h) + aoff + m * 2048 + k * 1024); } while (0)
; #define PG8_LDB(dst, b, h) do { _Pragma("unroll") for (int n = 0; n < 2; ++n) _Pragma("unroll") for (int k = 0; k < 2; ++k) dst[n][k] = *(const LAS bf16x8*)(lds + PG8_SB(b, h) + boff + n * 2048 + k * 1024); } while (0)
; #define PG8_MMA(ai, bj, At, Bt) do { __builtin_amdgcn_s_setprio(1); _Pragma("unroll") for (int m = 0; m < 4; ++m) _Pragma("unroll") for (int n = 0; n < 2; ++n) _Pragma("unroll") for (int k = 0; k < 2; ++k) \
;         acc[ai][bj][m][n] = __builtin_amdgcn_mfma_f32_16x16x32_bf16(Bt[n][k], At[m][k], acc[ai][bj][m][n], 0, 0, 0); __builtin_amdgcn_s_setprio(0); } while (0)
; #define PG8_WAIT_V(n) asm volatile("s_waitcnt vmcnt(" #n ")" ::: "memory")
; #define PG8_WAIT_L(n) asm volatile("s_waitcnt lgkmcnt(" #n ")" ::: "memory")
; #define PG8_BAR __builtin_amdgcn_s_barrier()
; #define PG8_SCHED __builtin_amdgcn_sched_barrier(0)
; template <class Epi, class Sched>
; __device__ __forceinline__ void gemm_phase(LAS unsigned char* lds, const Gemm g, const Sched S, const Epi E, const int tid) {
;     ...
;             PG8_WAIT_V(8); PG8_WAIT_L(0); PG8_BAR; PG8_MMA(1, 0, At, B0); PG8_MMA(1, 1, At, B1); PG8_BAR; PG8_SCHED;
;             PG8_LDB(B0, 1, 0); PG8_LDB(B1, 1, 1); PG8_SCHED; PG8_LDA(At, 1, 0); PG8_STAGE(PG8_SA(0, 1), a2 + hstepA, voffA);
;             PG8_WAIT_V(8); PG8_WAIT_L(0); PG8_BAR; PG8_MMA(0, 0, At, B0); PG8_MMA(0, 1, At, B1); PG8_BAR; PG8_SCHED;
	s_setprio 1
	v_mfma_f32_16x16x32_bf16 v[62:65], v[50:53], v[192:195], v[62:65]
	v_mfma_f32_16x16x32_bf16 v[58:61], v[150:153], v[192:195], v[58:61]
	v_mfma_f32_16x16x32_bf16 v[42:45], v[50:53], v[200:203], v[42:45]
	v_mfma_f32_16x16x32_bf16 v[38:41], v[150:153], v[200:203], v[38:41]
	v_mfma_f32_16x16x32_bf16 v[26:29], v[50:53], v[208:211], v[26:29]
	v_mfma_f32_16x16x32_bf16 v[22:25], v[150:153], v[208:211], v[22:25]
	v_mfma_f32_16x16x32_bf16 v[10:13], v[50:53], v[216:219], v[10:13]
	v_mfma_f32_16x16x32_bf16 v[6:9], v[150:153], v[216:219], v[6:9]
	v_mfma_f32_16x16x32_bf16 v[62:65], v[102:105], v[196:199], v[62:65]
	v_mfma_f32_16x16x32_bf16 v[58:61], v[154:157], v[196:199], v[58:61]
	v_mfma_f32_16x16x32_bf16 v[42:45], v[102:105], v[204:207], v[42:45]
	v_mfma_f32_16x16x32_bf16 v[38:41], v[154:157], v[204:207], v[38:41]
	v_mfma_f32_16x16x32_bf16 v[26:29], v[102:105], v[212:215], v[26:29]
	v_mfma_f32_16x16x32_bf16 v[22:25], v[154:157], v[212:215], v[22:25]
	v_mfma_f32_16x16x32_bf16 v[10:13], v[102:105], v[220:223], v[10:13]
	v_mfma_f32_16x16x32_bf16 v[6:9], v[154:157], v[220:223], v[6:9]
	v_mfma_f32_16x16x32_bf16 v[54:57], v[184:187], v[192:195], v[54:57]
	v_mfma_f32_16x16x32_bf16 v[46:49], v[158:161], v[200:203], v[46:49]
	v_mfma_f32_16x16x32_bf16 v[34:37], v[184:187], v[200:203], v[34:37]
	v_mfma_f32_16x16x32_bf16 v[30:33], v[158:161], v[208:211], v[30:33]
	v_mfma_f32_16x16x32_bf16 v[18:21], v[184:187], v[208:211], v[18:21]
	v_mfma_f32_16x16x32_bf16 v[14:17], v[158:161], v[216:219], v[14:17]
	v_mfma_f32_16x16x32_bf16 v[2:5], v[184:187], v[216:219], v[2:5]
	v_mfma_f32_16x16x32_bf16 v[50:53], v[158:161], v[192:195], v[66:69]
	v_mfma_f32_16x16x32_bf16 v[54:57], v[188:191], v[196:199], v[54:57]
	v_mfma_f32_16x16x32_bf16 v[46:49], v[180:183], v[204:207], v[46:49]
	v_mfma_f32_16x16x32_bf16 v[34:37], v[188:191], v[204:207], v[34:37]
	v_mfma_f32_16x16x32_bf16 v[30:33], v[180:183], v[212:215], v[30:33]
	v_mfma_f32_16x16x32_bf16 v[18:21], v[188:191], v[212:215], v[18:21]
	v_mfma_f32_16x16x32_bf16 v[14:17], v[180:183], v[220:223], v[14:17]
	v_mfma_f32_16x16x32_bf16 v[2:5], v[188:191], v[220:223], v[2:5]
	v_mfma_f32_16x16x32_bf16 v[50:53], v[180:183], v[196:199], v[50:53]
	s_setprio 0
	s_barrier
	s_add_i32 s83, 0, 0x18000
	s_add_i32 s84, 0, 0x1c000
	v_add_u32_e32 v154, s83, v165
	v_add_u32_e32 v167, s84, v165
	ds_read_b128 v[66:69], v154
	ds_read_b128 v[102:105], v154 offset:1024
	ds_read_b128 v[150:153], v154 offset:2048
	ds_read_b128 v[154:157], v154 offset:3072
	ds_read_b128 v[158:161], v167
	ds_read_b128 v[180:183], v167 offset:1024
	ds_read_b128 v[184:187], v167 offset:2048
	ds_read_b128 v[188:191], v167 offset:3072
	s_add_u32 s14, s14, 0x40000
	s_addc_u32 s15, s15, 0
	s_mov_b32 m0, s91
	v_lshl_add_u64 v[230:231], s[14:15], 0, v[138:139]
	ds_read_b128 v[192:195], v166 offset:32768
	ds_read_b128 v[196:199], v166 offset:33792
	ds_read_b128 v[200:203], v166 offset:34816
	ds_read_b128 v[204:207], v166 offset:35840
	ds_read_b128 v[208:211], v166 offset:36864
	ds_read_b128 v[212:215], v166 offset:37888
	ds_read_b128 v[216:219], v166 offset:38912
	ds_read_b128 v[220:223], v166 offset:39936
	global_load_lds_dwordx4 v[230:231], off
	v_lshl_add_u64 v[230:231], s[14:15], 0, v[142:143]
	s_mov_b32 m0, s68
	s_nop 0
	global_load_lds_dwordx4 v[230:231], off
	s_waitcnt vmcnt(8) lgkmcnt(0)
	s_barrier
	s_setprio 1
	v_mfma_f32_16x16x32_bf16 v[130:133], v[66:69], v[192:195], v[130:133]
	v_mfma_f32_16x16x32_bf16 v[126:129], v[150:153], v[192:195], v[126:129]
	v_mfma_f32_16x16x32_bf16 v[114:117], v[66:69], v[200:203], v[114:117]
	v_mfma_f32_16x16x32_bf16 v[110:113], v[150:153], v[200:203], v[110:113]
	v_mfma_f32_16x16x32_bf16 v[94:97], v[66:69], v[208:211], v[94:97]
	v_mfma_f32_16x16x32_bf16 v[90:93], v[150:153], v[208:211], v[90:93]
	v_mfma_f32_16x16x32_bf16 v[78:81], v[66:69], v[216:219], v[78:81]
	v_mfma_f32_16x16x32_bf16 v[74:77], v[150:153], v[216:219], v[74:77]
	v_mfma_f32_16x16x32_bf16 v[130:133], v[102:105], v[196:199], v[130:133]
	v_mfma_f32_16x16x32_bf16 v[126:129], v[154:157], v[196:199], v[126:129]
	v_mfma_f32_16x16x32_bf16 v[114:117], v[102:105], v[204:207], v[114:117]
	v_mfma_f32_16x16x32_bf16 v[110:113], v[154:157], v[204:207], v[110:113]
	v_mfma_f32_16x16x32_bf16 v[94:97], v[102:105], v[212:215], v[94:97]
	v_mfma_f32_16x16x32_bf16 v[90:93], v[154:157], v[212:215], v[90:93]
	v_mfma_f32_16x16x32_bf16 v[78:81], v[102:105], v[220:223], v[78:81]
	v_mfma_f32_16x16x32_bf16 v[74:77], v[154:157], v[220:223], v[74:77]
	v_mfma_f32_16x16x32_bf16 v[134:137], v[158:161], v[192:195], v[134:137]
	v_mfma_f32_16x16x32_bf16 v[122:125], v[184:187], v[192:195], v[122:125]
	v_mfma_f32_16x16x32_bf16 v[118:121], v[158:161], v[200:203], v[118:121]
	v_mfma_f32_16x16x32_bf16 v[106:109], v[184:187], v[200:203], v[106:109]
	v_mfma_f32_16x16x32_bf16 v[98:101], v[158:161], v[208:211], v[98:101]
	v_mfma_f32_16x16x32_bf16 v[86:89], v[184:187], v[208:211], v[86:89]
	v_mfma_f32_16x16x32_bf16 v[82:85], v[158:161], v[216:219], v[82:85]
	v_mfma_f32_16x16x32_bf16 v[70:73], v[184:187], v[216:219], v[70:73]
	v_mfma_f32_16x16x32_bf16 v[134:137], v[180:183], v[196:199], v[134:137]
	v_mfma_f32_16x16x32_bf16 v[122:125], v[188:191], v[196:199], v[122:125]
	v_mfma_f32_16x16x32_bf16 v[118:121], v[180:183], v[204:207], v[118:121]
	v_mfma_f32_16x16x32_bf16 v[106:109], v[188:191], v[204:207], v[106:109]
	v_mfma_f32_16x16x32_bf16 v[98:101], v[180:183], v[212:215], v[98:101]
	v_mfma_f32_16x16x32_bf16 v[86:89], v[188:191], v[212:215], v[86:89]
	v_mfma_f32_16x16x32_bf16 v[82:85], v[180:183], v[220:223], v[82:85]
	v_mfma_f32_16x16x32_bf16 v[70:73], v[188:191], v[220:223], v[70:73]
	s_setprio 0
	s_barrier
; #define PG8_STAGE(bufoff, gbase, voff) do { _Pragma("unroll") for (int _i = 0; _i < 2; ++_i) \
;         __builtin_amdgcn_global_load_lds((const unsigned*)((const char*)(gbase) + (voff)[_i]), (LAS unsigned*)(lds + (bufoff) + ldsw + _i * 8192), 16, 0, 0); } while (0)
; #define PG8_LDA(dst, b, h) do { _Pragma("unroll") for (int m = 0; m < 4; ++m) _Pragma("unroll") for (int k = 0; k < 2; ++k) dst[m][k] = *(const LAS bf16x8*)(lds + PG8_SA(b, h) + aoff + m * 2048 + k * 1024); } while (0)
; #define PG8_MMA(ai, bj, At, Bt) do { __builtin_amdgcn_s_setprio(1); _Pragma("unroll") for (int m = 0; m < 4; ++m) _Pragma("unroll") for (int n = 0; n < 2; ++n) _Pragma("unroll") for (int k = 0; k < 2; ++k) \
;         acc[ai][bj][m][n] = __builtin_amdgcn_mfma_f32_16x16x32_bf16(Bt[n][k], At[m][k], acc[ai][bj][m][n], 0, 0, 0); __builtin_amdgcn_s_setprio(0); } while (0)
; #define PG8_WAIT_V(n) asm volatile("s_waitcnt vmcnt(" #n ")" ::: "memory")
; #define PG8_WAIT_L(n) asm volatile("s_waitcnt lgkmcnt(" #n ")" ::: "memory")
; #define PG8_BAR __builtin_amdgcn_s_barrier()
; #define PG8_SCHED __builtin_amdgcn_sched_barrier(0)
; template <class Epi, class Sched>
; __device__ __forceinline__ void gemm_phase(LAS unsigned char* lds, const Gemm g, const Sched S, const Epi E, const int tid) {
;     ...
;             PG8_LDA(At, 1, 1); PG8_STAGE(PG8_SB(1, 0), b3, voffB); PG8_STAGE(PG8_SB(1, 1), b3 + hstepB, voffB); PG8_STAGE(PG8_SA(1, 0), a3, voffA);
;             PG8_WAIT_V(8); PG8_WAIT_L(0); PG8_BAR; PG8_MMA(1, 0, At, B0); PG8_MMA(1, 1, At, B1); PG8_BAR; PG8_SCHED;
;         }
	s_add_i32 s14, s83, s37
	v_lshl_add_u64 v[162:163], v[162:163], 0, s[64:65]
	s_mov_b32 m0, s14
	ds_read_b128 v[192:195], v166 offset:49152
	ds_read_b128 v[196:199], v166 offset:50176
	ds_read_b128 v[200:203], v166 offset:51200
	ds_read_b128 v[204:207], v166 offset:52224
	ds_read_b128 v[208:211], v166 offset:53248
	ds_read_b128 v[212:215], v166 offset:54272
	ds_read_b128 v[216:219], v166 offset:55296
	ds_read_b128 v[220:223], v166 offset:56320
	global_load_lds_dwordx4 v[162:163], off
	s_add_i32 m0, s14, 0x2000
	s_add_u32 s12, s12, 0x40080
	v_lshl_add_u64 v[162:163], v[224:225], 0, s[64:65]
	s_addc_u32 s13, s13, 0
	s_add_i32 s14, s84, s37
	global_load_lds_dwordx4 v[162:163], off
	v_lshl_add_u64 v[162:163], s[12:13], 0, v[140:141]
	s_mov_b32 m0, s14
	s_nop 0
	global_load_lds_dwordx4 v[162:163], off
	v_lshl_add_u64 v[162:163], s[12:13], 0, v[144:145]
	s_add_i32 m0, s14, 0x2000
	s_nop 0
	global_load_lds_dwordx4 v[162:163], off
	v_lshl_add_u64 v[162:163], v[226:227], 0, s[64:65]
	s_mov_b32 m0, s29
	s_nop 0
	global_load_lds_dwordx4 v[162:163], off
	v_lshl_add_u64 v[162:163], v[228:229], 0, s[64:65]
	s_mov_b32 m0, s92
	s_nop 0
	global_load_lds_dwordx4 v[162:163], off
	s_waitcnt vmcnt(8) lgkmcnt(0)
	s_barrier
	s_setprio 1
	v_mfma_f32_16x16x32_bf16 v[62:65], v[66:69], v[192:195], v[62:65]
	v_mfma_f32_16x16x32_bf16 v[58:61], v[150:153], v[192:195], v[58:61]
	v_mfma_f32_16x16x32_bf16 v[42:45], v[66:69], v[200:203], v[42:45]
	v_mfma_f32_16x16x32_bf16 v[38:41], v[150:153], v[200:203], v[38:41]
	v_mfma_f32_16x16x32_bf16 v[26:29], v[66:69], v[208:211], v[26:29]
	v_mfma_f32_16x16x32_bf16 v[22:25], v[150:153], v[208:211], v[22:25]
	v_mfma_f32_16x16x32_bf16 v[10:13], v[66:69], v[216:219], v[10:13]
	v_mfma_f32_16x16x32_bf16 v[6:9], v[150:153], v[216:219], v[6:9]
	v_mfma_f32_16x16x32_bf16 v[62:65], v[102:105], v[196:199], v[62:65]
	v_mfma_f32_16x16x32_bf16 v[58:61], v[154:157], v[196:199], v[58:61]
	v_mfma_f32_16x16x32_bf16 v[42:45], v[102:105], v[204:207], v[42:45]
	v_mfma_f32_16x16x32_bf16 v[38:41], v[154:157], v[204:207], v[38:41]
	v_mfma_f32_16x16x32_bf16 v[26:29], v[102:105], v[212:215], v[26:29]
	v_mfma_f32_16x16x32_bf16 v[22:25], v[154:157], v[212:215], v[22:25]
	v_mfma_f32_16x16x32_bf16 v[10:13], v[102:105], v[220:223], v[10:13]
	v_mfma_f32_16x16x32_bf16 v[6:9], v[154:157], v[220:223], v[6:9]
	v_mfma_f32_16x16x32_bf16 v[50:53], v[158:161], v[192:195], v[50:53]
	v_mfma_f32_16x16x32_bf16 v[66:69], v[180:183], v[196:199], v[50:53]
	v_mfma_f32_16x16x32_bf16 v[50:53], v[184:187], v[192:195], v[54:57]
	v_mfma_f32_16x16x32_bf16 v[46:49], v[158:161], v[200:203], v[46:49]
	v_mfma_f32_16x16x32_bf16 v[34:37], v[184:187], v[200:203], v[34:37]
	v_mfma_f32_16x16x32_bf16 v[30:33], v[158:161], v[208:211], v[30:33]
	v_mfma_f32_16x16x32_bf16 v[18:21], v[184:187], v[208:211], v[18:21]
	v_mfma_f32_16x16x32_bf16 v[14:17], v[158:161], v[216:219], v[14:17]
	v_mfma_f32_16x16x32_bf16 v[2:5], v[184:187], v[216:219], v[2:5]
	v_mfma_f32_16x16x32_bf16 v[54:57], v[188:191], v[196:199], v[50:53]
	v_mfma_f32_16x16x32_bf16 v[46:49], v[180:183], v[204:207], v[46:49]
	v_mfma_f32_16x16x32_bf16 v[34:37], v[188:191], v[204:207], v[34:37]
	v_mfma_f32_16x16x32_bf16 v[30:33], v[180:183], v[212:215], v[30:33]
	v_mfma_f32_16x16x32_bf16 v[18:21], v[188:191], v[212:215], v[18:21]
	v_mfma_f32_16x16x32_bf16 v[14:17], v[180:183], v[220:223], v[14:17]
	v_mfma_f32_16x16x32_bf16 v[2:5], v[188:191], v[220:223], v[2:5]
	s_setprio 0
	s_barrier
	s_add_i32 s82, s82, 2
	s_add_u32 s49, s49, 0x100
	s_addc_u32 s62, s62, 0
	s_add_u32 s10, s10, 0x100
	s_addc_u32 s11, s11, 0
	s_cmp_gt_u32 s82, 13
	s_cbranch_scc0 .LBB0_471
	s_and_b64 vcc, exec, s[18:19]
	s_cbranch_vccz .LBB0_474
	s_barrier

; #define PG8_STAGE(bufoff, gbase, voff) do { _Pragma("unroll") for (int _i = 0; _i < 2; ++_i) \
;         __builtin_amdgcn_global_load_lds((const unsigned*)((const char*)(gbase) + (voff)[_i]), (LAS unsigned*)(lds + (bufoff) + ldsw + _i * 8192), 16, 0, 0); } while (0)
; #define PG8_LDA(dst, b, h) do { _Pragma("unroll") for (int m = 0; m < 4; ++m) _Pragma("unroll") for (int k = 0; k < 2; ++k) dst[m][k] = *(const LAS bf16x8*)(lds + PG8_SA(b, h) + aoff + m * 2048 + k * 1024); } while (0)
; #define PG8_LDB(dst, b, h) do { _Pragma("unroll") for (int n = 0; n < 2; ++n) _Pragma("unroll") for (int k = 0; k < 2; ++k) dst[n][k] = *(const LAS bf16x8*)(lds + PG8_SB(b, h) + boff + n * 2048 + k * 1024); } while (0)
; #define PG8_MMA(ai, bj, At, Bt) do { __builtin_amdgcn_s_setprio(1); _Pragma("unroll") for (int m = 0; m < 4; ++m) _Pragma("unroll") for (int n = 0; n < 2; ++n) _Pragma("unroll") for (int k = 0; k < 2; ++k) \
;         acc[ai][bj][m][n] = __builtin_amdgcn_mfma_f32_16x16x32_bf16(Bt[n][k], At[m][k], acc[ai][bj][m][n], 0, 0, 0); __builtin_amdgcn_s_setprio(0); } while (0)
; #define PG8_WAIT_V(n) asm volatile("s_waitcnt vmcnt(" #n ")" ::: "memory")
; #define PG8_WAIT_L(n) asm volatile("s_waitcnt lgkmcnt(" #n ")" ::: "memory")
; #define PG8_BAR __builtin_amdgcn_s_barrier()
; #define PG8_SCHED __builtin_amdgcn_sched_barrier(0)
; template <class Epi, class Sched>
; __device__ __forceinline__ void gemm_phase(LAS unsigned char* lds, const Gemm g, const Sched S, const Epi E, const int tid) {
;     ...
;         for (int t = 0; t < nt; t += 2) {
;             const bool last = (t == nt - 2);
;             const char* a1 = cA + (size_t)(t + 1) * kstep;
;             const char* a2 = last ? nA : cA + (size_t)(t + 2) * kstep; const char* b2 = last ? nB : cB + (size_t)(t + 2) * kstep;
;             const char* a3 = a2 + kstep; const char* b3 = b2 + kstep;
;             PG8_LDB(B0, 0, 0); PG8_LDB(B1, 0, 1); PG8_SCHED; PG8_LDA(At, 0, 0); PG8_STAGE(PG8_SA(1, 1), a1 + hstepA, voffA);
;             PG8_WAIT_V(8); PG8_WAIT_L(0); PG8_BAR; PG8_MMA(0, 0, At, B0); PG8_MMA(0, 1, At, B1); PG8_BAR; PG8_SCHED;
;             PG8_LDA(At, 0, 1); PG8_STAGE(PG8_SB(0, 0), b2, voffB); PG8_STAGE(PG8_SB(0, 1), b2 + hstepB, voffB); PG8_STAGE(PG8_SA(0, 0), a2, voffA);
;             PG8_WAIT_V(8); PG8_WAIT_L(0); PG8_BAR; PG8_MMA(1, 0, At, B0); PG8_MMA(1, 1, At, B1); PG8_BAR; PG8_SCHED;
.LBB0_778:
	s_add_i32 s94, s20, 2
	s_add_u32 s95, s18, 0x80
	s_addc_u32 s21, s19, 0
	s_add_i32 vcc_lo, 0, 0x10000
	s_cmp_eq_u32 s69, s20
	s_cselect_b32 s21, s9, s21
	s_cselect_b32 s20, s8, s95
	s_cselect_b32 s97, s17, s93
	s_cselect_b32 s96, s16, s92
	s_add_i32 s95, 0, 0x14000
	v_add_u32_e32 v142, vcc_lo, v198
	v_add_u32_e32 v167, s95, v198
	ds_read_b128 v[126:129], v142
	ds_read_b128 v[134:137], v142 offset:1024
	ds_read_b128 v[138:141], v142 offset:2048
	ds_read_b128 v[142:145], v142 offset:3072
	ds_read_b128 v[146:149], v167
	ds_read_b128 v[150:153], v167 offset:1024
	ds_read_b128 v[154:157], v167 offset:2048
	ds_read_b128 v[186:189], v167 offset:3072
	v_lshl_add_u64 v[224:225], s[18:19], 0, v[184:185]
	s_add_i32 m0, s37, 0xc000
	ds_read_b128 v[190:193], v199
	ds_read_b128 v[194:197], v199 offset:1024
	ds_read_b128 v[200:203], v199 offset:2048
	ds_read_b128 v[204:207], v199 offset:3072
	ds_read_b128 v[208:211], v199 offset:4096
	ds_read_b128 v[212:215], v199 offset:5120
	ds_read_b128 v[216:219], v199 offset:6144
	ds_read_b128 v[220:223], v199 offset:7168
	global_load_lds_dwordx4 v[224:225], off
	v_lshl_add_u64 v[224:225], s[18:19], 0, v[182:183]
	s_add_i32 m0, s37, 0xe000
	s_nop 0
	global_load_lds_dwordx4 v[224:225], off
	s_waitcnt vmcnt(8) lgkmcnt(0)
	s_barrier
	s_setprio 1
	v_mfma_f32_16x16x32_bf16 v[130:133], v[126:129], v[190:193], v[130:133]
	v_mfma_f32_16x16x32_bf16 v[122:125], v[138:141], v[190:193], v[122:125]
	v_mfma_f32_16x16x32_bf16 v[110:113], v[126:129], v[200:203], v[110:113]
	v_mfma_f32_16x16x32_bf16 v[106:109], v[138:141], v[200:203], v[106:109]
	v_mfma_f32_16x16x32_bf16 v[94:97], v[126:129], v[208:211], v[94:97]
	v_mfma_f32_16x16x32_bf16 v[90:93], v[138:141], v[208:211], v[90:93]
	v_mfma_f32_16x16x32_bf16 v[78:81], v[126:129], v[216:219], v[78:81]
	v_mfma_f32_16x16x32_bf16 v[74:77], v[138:141], v[216:219], v[74:77]
	v_mfma_f32_16x16x32_bf16 v[130:133], v[134:137], v[194:197], v[130:133]
	v_mfma_f32_16x16x32_bf16 v[122:125], v[142:145], v[194:197], v[122:125]
	v_mfma_f32_16x16x32_bf16 v[110:113], v[134:137], v[204:207], v[110:113]
	v_mfma_f32_16x16x32_bf16 v[106:109], v[142:145], v[204:207], v[106:109]
	v_mfma_f32_16x16x32_bf16 v[94:97], v[134:137], v[212:215], v[94:97]
	v_mfma_f32_16x16x32_bf16 v[90:93], v[142:145], v[212:215], v[90:93]
	v_mfma_f32_16x16x32_bf16 v[78:81], v[134:137], v[220:223], v[78:81]
	v_mfma_f32_16x16x32_bf16 v[74:77], v[142:145], v[220:223], v[74:77]
	v_mfma_f32_16x16x32_bf16 v[118:121], v[146:149], v[190:193], v[118:121]
	v_mfma_f32_16x16x32_bf16 v[114:117], v[154:157], v[190:193], v[114:117]
	v_mfma_f32_16x16x32_bf16 v[102:105], v[146:149], v[200:203], v[102:105]
	v_mfma_f32_16x16x32_bf16 v[98:101], v[154:157], v[200:203], v[98:101]
	v_mfma_f32_16x16x32_bf16 v[86:89], v[146:149], v[208:211], v[86:89]
	v_mfma_f32_16x16x32_bf16 v[82:85], v[154:157], v[208:211], v[82:85]
	v_mfma_f32_16x16x32_bf16 v[70:73], v[146:149], v[216:219], v[70:73]
	v_mfma_f32_16x16x32_bf16 v[66:69], v[154:157], v[216:219], v[66:69]
	v_mfma_f32_16x16x32_bf16 v[118:121], v[150:153], v[194:197], v[118:121]
	v_mfma_f32_16x16x32_bf16 v[114:117], v[186:189], v[194:197], v[114:117]
	v_mfma_f32_16x16x32_bf16 v[102:105], v[150:153], v[204:207], v[102:105]
	v_mfma_f32_16x16x32_bf16 v[98:101], v[186:189], v[204:207], v[98:101]
	v_mfma_f32_16x16x32_bf16 v[86:89], v[150:153], v[212:215], v[86:89]
	v_mfma_f32_16x16x32_bf16 v[82:85], v[186:189], v[212:215], v[82:85]
	v_mfma_f32_16x16x32_bf16 v[70:73], v[150:153], v[220:223], v[70:73]
	v_mfma_f32_16x16x32_bf16 v[66:69], v[186:189], v[220:223], v[66:69]
	s_setprio 0
	s_barrier
	s_add_i32 vcc_lo, vcc_lo, s29
	v_lshl_add_u64 v[224:225], s[96:97], 0, v[160:161]
	s_mov_b32 m0, vcc_lo
	ds_read_b128 v[190:193], v199 offset:16384
	ds_read_b128 v[194:197], v199 offset:17408
	ds_read_b128 v[200:203], v199 offset:18432
	ds_read_b128 v[204:207], v199 offset:19456
	ds_read_b128 v[208:211], v199 offset:20480
	ds_read_b128 v[212:215], v199 offset:21504
	ds_read_b128 v[216:219], v199 offset:22528
	ds_read_b128 v[220:223], v199 offset:23552
	global_load_lds_dwordx4 v[224:225], off
	s_add_i32 m0, vcc_lo, 0x2000
	v_lshl_add_u64 v[226:227], s[96:97], 0, v[164:165]
	s_add_u32 s96, s96, s62
	s_addc_u32 s97, s97, 0
	s_add_i32 s95, s95, s29
	global_load_lds_dwordx4 v[226:227], off
	v_lshl_add_u64 v[228:229], s[96:97], 0, v[160:161]
	s_mov_b32 m0, s95
	v_lshl_add_u64 v[230:231], s[96:97], 0, v[164:165]
	global_load_lds_dwordx4 v[228:229], off
	s_add_i32 m0, s95, 0x2000
	v_lshl_add_u64 v[232:233], s[20:21], 0, v[158:159]
	global_load_lds_dwordx4 v[230:231], off
	s_mov_b32 m0, s37
	v_lshl_add_u64 v[234:235], s[20:21], 0, v[162:163]
	global_load_lds_dwordx4 v[232:233], off
	s_mov_b32 m0, s40
	s_nop 0
	global_load_lds_dwordx4 v[234:235], off
	s_waitcnt vmcnt(8) lgkmcnt(0)
	s_barrier
; #define PG8_STAGE(bufoff, gbase, voff) do { _Pragma("unroll") for (int _i = 0; _i < 2; ++_i) \
;         __builtin_amdgcn_global_load_lds((const unsigned*)((const char*)(gbase) + (voff)[_i]), (LAS unsigned*)(lds + (bufoff) + ldsw + _i * 8192), 16, 0, 0); } while (0)
; #define PG8_LDA(dst, b, h) do { _Pragma("unroll") for (int m = 0; m < 4; ++m) _Pragma("unroll") for (int k = 0; k < 2; ++k) dst[m][k] = *(const LAS bf16x8*)(lds + PG8_SA(b, h) + aoff + m * 2048 + k * 1024); } while (0)
; #define PG8_LDB(dst, b, h) do { _Pragma("unroll") for (int n = 0; n < 2; ++n) _Pragma("unroll") for (int k = 0; k < 2; ++k) dst[n][k] = *(const LAS bf16x8*)(lds + PG8_SB(b, h) + boff + n * 2048 + k * 1024); } while (0)
; #define PG8_MMA(ai, bj, At, Bt) do { __builtin_amdgcn_s_setprio(1); _Pragma("unroll") for (int m = 0; m < 4; ++m) _Pragma("unroll") for (int n = 0; n < 2; ++n) _Pragma("unroll") for (int k = 0; k < 2; ++k) \
;         acc[ai][bj][m][n] = __builtin_amdgcn_mfma_f32_16x16x32_bf16(Bt[n][k], At[m][k], acc[ai][bj][m][n], 0, 0, 0); __builtin_amdgcn_s_setprio(0); } while (0)
; #define PG8_WAIT_V(n) asm volatile("s_waitcnt vmcnt(" #n ")" ::: "memory")
; #define PG8_WAIT_L(n) asm volatile("s_waitcnt lgkmcnt(" #n ")" ::: "memory")
; #define PG8_BAR __builtin_amdgcn_s_barrier()
; #define PG8_SCHED __builtin_amdgcn_sched_barrier(0)
; template <class Epi, class Sched>
; __device__ __forceinline__ void gemm_phase(LAS unsigned char* lds, const Gemm g, const Sched S, const Epi E, const int tid) {
;     ...
;             PG8_WAIT_V(8); PG8_WAIT_L(0); PG8_BAR; PG8_MMA(1, 0, At, B0); PG8_MMA(1, 1, At, B1); PG8_BAR; PG8_SCHED;
;             PG8_LDB(B0, 1, 0); PG8_LDB(B1, 1, 1); PG8_SCHED; PG8_LDA(At, 1, 0); PG8_STAGE(PG8_SA(0, 1), a2 + hstepA, voffA);
;             PG8_WAIT_V(8); PG8_WAIT_L(0); PG8_BAR; PG8_MMA(0, 0, At, B0); PG8_MMA(0, 1, At, B1); PG8_BAR; PG8_SCHED;
	s_setprio 1
	v_mfma_f32_16x16x32_bf16 v[62:65], v[126:129], v[190:193], v[62:65]
	v_mfma_f32_16x16x32_bf16 v[58:61], v[138:141], v[190:193], v[58:61]
	v_mfma_f32_16x16x32_bf16 v[46:49], v[126:129], v[200:203], v[46:49]
	v_mfma_f32_16x16x32_bf16 v[42:45], v[138:141], v[200:203], v[42:45]
	v_mfma_f32_16x16x32_bf16 v[30:33], v[126:129], v[208:211], v[30:33]
	v_mfma_f32_16x16x32_bf16 v[26:29], v[138:141], v[208:211], v[26:29]
	v_mfma_f32_16x16x32_bf16 v[14:17], v[126:129], v[216:219], v[14:17]
	v_mfma_f32_16x16x32_bf16 v[10:13], v[138:141], v[216:219], v[10:13]
	v_mfma_f32_16x16x32_bf16 v[62:65], v[134:137], v[194:197], v[62:65]
	v_mfma_f32_16x16x32_bf16 v[58:61], v[142:145], v[194:197], v[58:61]
	v_mfma_f32_16x16x32_bf16 v[46:49], v[134:137], v[204:207], v[46:49]
	v_mfma_f32_16x16x32_bf16 v[42:45], v[142:145], v[204:207], v[42:45]
	v_mfma_f32_16x16x32_bf16 v[30:33], v[134:137], v[212:215], v[30:33]
	v_mfma_f32_16x16x32_bf16 v[26:29], v[142:145], v[212:215], v[26:29]
	v_mfma_f32_16x16x32_bf16 v[14:17], v[134:137], v[220:223], v[14:17]
	v_mfma_f32_16x16x32_bf16 v[10:13], v[142:145], v[220:223], v[10:13]
	v_mfma_f32_16x16x32_bf16 v[54:57], v[146:149], v[190:193], v[54:57]
	v_mfma_f32_16x16x32_bf16 v[50:53], v[154:157], v[190:193], v[50:53]
	v_mfma_f32_16x16x32_bf16 v[38:41], v[146:149], v[200:203], v[38:41]
	v_mfma_f32_16x16x32_bf16 v[34:37], v[154:157], v[200:203], v[34:37]
	v_mfma_f32_16x16x32_bf16 v[22:25], v[146:149], v[208:211], v[22:25]
	v_mfma_f32_16x16x32_bf16 v[18:21], v[154:157], v[208:211], v[18:21]
	v_mfma_f32_16x16x32_bf16 v[6:9], v[146:149], v[216:219], v[6:9]
	v_mfma_f32_16x16x32_bf16 v[2:5], v[154:157], v[216:219], v[2:5]
	v_mfma_f32_16x16x32_bf16 v[54:57], v[150:153], v[194:197], v[54:57]
	v_mfma_f32_16x16x32_bf16 v[50:53], v[186:189], v[194:197], v[50:53]
	v_mfma_f32_16x16x32_bf16 v[38:41], v[150:153], v[204:207], v[38:41]
	v_mfma_f32_16x16x32_bf16 v[34:37], v[186:189], v[204:207], v[34:37]
	v_mfma_f32_16x16x32_bf16 v[22:25], v[150:153], v[212:215], v[22:25]
	v_mfma_f32_16x16x32_bf16 v[18:21], v[186:189], v[212:215], v[18:21]
	v_mfma_f32_16x16x32_bf16 v[6:9], v[150:153], v[220:223], v[6:9]
	v_mfma_f32_16x16x32_bf16 v[2:5], v[186:189], v[220:223], v[2:5]
	s_setprio 0
	s_barrier
	s_add_i32 s95, 0, 0x18000
	s_add_i32 s96, 0, 0x1c000
	v_add_u32_e32 v142, s95, v198
	v_add_u32_e32 v167, s96, v198
	ds_read_b128 v[126:129], v142
	ds_read_b128 v[134:137], v142 offset:1024
	ds_read_b128 v[138:141], v142 offset:2048
	ds_read_b128 v[142:145], v142 offset:3072
	ds_read_b128 v[146:149], v167
	ds_read_b128 v[150:153], v167 offset:1024
	ds_read_b128 v[154:157], v167 offset:2048
	ds_read_b128 v[186:189], v167 offset:3072
	s_add_u32 s20, s20, s62
	s_addc_u32 s21, s21, 0
	s_mov_b32 m0, s41
	v_lshl_add_u64 v[246:247], s[20:21], 0, v[158:159]
	ds_read_b128 v[190:193], v199 offset:32768
	ds_read_b128 v[194:197], v199 offset:33792
	ds_read_b128 v[200:203], v199 offset:34816
	ds_read_b128 v[204:207], v199 offset:35840
	ds_read_b128 v[208:211], v199 offset:36864
	ds_read_b128 v[212:215], v199 offset:37888
	ds_read_b128 v[216:219], v199 offset:38912
	ds_read_b128 v[220:223], v199 offset:39936
	global_load_lds_dwordx4 v[246:247], off
	v_lshl_add_u64 v[246:247], s[20:21], 0, v[162:163]
	s_mov_b32 m0, s42
	s_nop 0
	global_load_lds_dwordx4 v[246:247], off
	s_waitcnt vmcnt(8) lgkmcnt(0)
	s_barrier
	s_setprio 1
	v_mfma_f32_16x16x32_bf16 v[130:133], v[126:129], v[190:193], v[130:133]
	v_mfma_f32_16x16x32_bf16 v[122:125], v[138:141], v[190:193], v[122:125]
	v_mfma_f32_16x16x32_bf16 v[110:113], v[126:129], v[200:203], v[110:113]
	v_mfma_f32_16x16x32_bf16 v[106:109], v[138:141], v[200:203], v[106:109]
	v_mfma_f32_16x16x32_bf16 v[94:97], v[126:129], v[208:211], v[94:97]
	v_mfma_f32_16x16x32_bf16 v[90:93], v[138:141], v[208:211], v[90:93]
	v_mfma_f32_16x16x32_bf16 v[78:81], v[126:129], v[216:219], v[78:81]
	v_mfma_f32_16x16x32_bf16 v[74:77], v[138:141], v[216:219], v[74:77]
	v_mfma_f32_16x16x32_bf16 v[130:133], v[134:137], v[194:197], v[130:133]
	v_mfma_f32_16x16x32_bf16 v[122:125], v[142:145], v[194:197], v[122:125]
	v_mfma_f32_16x16x32_bf16 v[110:113], v[134:137], v[204:207], v[110:113]
	v_mfma_f32_16x16x32_bf16 v[106:109], v[142:145], v[204:207], v[106:109]
	v_mfma_f32_16x16x32_bf16 v[94:97], v[134:137], v[212:215], v[94:97]
	v_mfma_f32_16x16x32_bf16 v[90:93], v[142:145], v[212:215], v[90:93]
	v_mfma_f32_16x16x32_bf16 v[78:81], v[134:137], v[220:223], v[78:81]
	v_mfma_f32_16x16x32_bf16 v[74:77], v[142:145], v[220:223], v[74:77]
	v_mfma_f32_16x16x32_bf16 v[118:121], v[146:149], v[190:193], v[118:121]
	v_mfma_f32_16x16x32_bf16 v[114:117], v[154:157], v[190:193], v[114:117]
	v_mfma_f32_16x16x32_bf16 v[102:105], v[146:149], v[200:203], v[102:105]
	v_mfma_f32_16x16x32_bf16 v[98:101], v[154:157], v[200:203], v[98:101]
	v_mfma_f32_16x16x32_bf16 v[86:89], v[146:149], v[208:211], v[86:89]
	v_mfma_f32_16x16x32_bf16 v[82:85], v[154:157], v[208:211], v[82:85]
	v_mfma_f32_16x16x32_bf16 v[70:73], v[146:149], v[216:219], v[70:73]
	v_mfma_f32_16x16x32_bf16 v[66:69], v[154:157], v[216:219], v[66:69]
	v_mfma_f32_16x16x32_bf16 v[118:121], v[150:153], v[194:197], v[118:121]
	v_mfma_f32_16x16x32_bf16 v[114:117], v[186:189], v[194:197], v[114:117]
	v_mfma_f32_16x16x32_bf16 v[102:105], v[150:153], v[204:207], v[102:105]
	v_mfma_f32_16x16x32_bf16 v[98:101], v[186:189], v[204:207], v[98:101]
	v_mfma_f32_16x16x32_bf16 v[86:89], v[150:153], v[212:215], v[86:89]
	v_mfma_f32_16x16x32_bf16 v[82:85], v[186:189], v[212:215], v[82:85]
	v_mfma_f32_16x16x32_bf16 v[70:73], v[150:153], v[220:223], v[70:73]
	v_mfma_f32_16x16x32_bf16 v[66:69], v[186:189], v[220:223], v[66:69]
	s_setprio 0
	s_barrier
; #define PG8_STAGE(bufoff, gbase, voff) do { _Pragma("unroll") for (int _i = 0; _i < 2; ++_i) \
;         __builtin_amdgcn_global_load_lds((const unsigned*)((const char*)(gbase) + (voff)[_i]), (LAS unsigned*)(lds + (bufoff) + ldsw + _i * 8192), 16, 0, 0); } while (0)
; #define PG8_LDA(dst, b, h) do { _Pragma("unroll") for (int m = 0; m < 4; ++m) _Pragma("unroll") for (int k = 0; k < 2; ++k) dst[m][k] = *(const LAS bf16x8*)(lds + PG8_SA(b, h) + aoff + m * 2048 + k * 1024); } while (0)
; #define PG8_MMA(ai, bj, At, Bt) do { __builtin_amdgcn_s_setprio(1); _Pragma("unroll") for (int m = 0; m < 4; ++m) _Pragma("unroll") for (int n = 0; n < 2; ++n) _Pragma("unroll") for (int k = 0; k < 2; ++k) \
;         acc[ai][bj][m][n] = __builtin_amdgcn_mfma_f32_16x16x32_bf16(Bt[n][k], At[m][k], acc[ai][bj][m][n], 0, 0, 0); __builtin_amdgcn_s_setprio(0); } while (0)
; #define PG8_WAIT_V(n) asm volatile("s_waitcnt vmcnt(" #n ")" ::: "memory")
; #define PG8_WAIT_L(n) asm volatile("s_waitcnt lgkmcnt(" #n ")" ::: "memory")
; #define PG8_BAR __builtin_amdgcn_s_barrier()
; #define PG8_SCHED __builtin_amdgcn_sched_barrier(0)
; template <class Epi, class Sched>
; __device__ __forceinline__ void gemm_phase(LAS unsigned char* lds, const Gemm g, const Sched S, const Epi E, const int tid) {
;     ...
;             PG8_LDA(At, 1, 1); PG8_STAGE(PG8_SB(1, 0), b3, voffB); PG8_STAGE(PG8_SB(1, 1), b3 + hstepB, voffB); PG8_STAGE(PG8_SA(1, 0), a3, voffA);
;             PG8_WAIT_V(8); PG8_WAIT_L(0); PG8_BAR; PG8_MMA(1, 0, At, B0); PG8_MMA(1, 1, At, B1); PG8_BAR; PG8_SCHED;
;         }
	s_add_i32 s20, s95, s29
	v_lshl_add_u64 v[224:225], v[224:225], 0, s[64:65]
	s_mov_b32 m0, s20
	ds_read_b128 v[190:193], v199 offset:49152
	ds_read_b128 v[194:197], v199 offset:50176
	ds_read_b128 v[200:203], v199 offset:51200
	ds_read_b128 v[204:207], v199 offset:52224
	ds_read_b128 v[208:211], v199 offset:53248
	ds_read_b128 v[212:215], v199 offset:54272
	ds_read_b128 v[216:219], v199 offset:55296
	ds_read_b128 v[220:223], v199 offset:56320
	global_load_lds_dwordx4 v[224:225], off
	v_lshl_add_u64 v[224:225], v[226:227], 0, s[64:65]
	s_add_i32 m0, s20, 0x2000
	s_add_i32 s20, s96, s29
	global_load_lds_dwordx4 v[224:225], off
	v_lshl_add_u64 v[224:225], v[228:229], 0, s[64:65]
	s_mov_b32 m0, s20
	s_nop 0
	global_load_lds_dwordx4 v[224:225], off
	v_lshl_add_u64 v[224:225], v[230:231], 0, s[64:65]
	s_add_i32 m0, s20, 0x2000
	s_nop 0
	global_load_lds_dwordx4 v[224:225], off
	v_lshl_add_u64 v[224:225], v[232:233], 0, s[64:65]
	s_mov_b32 m0, s45
	s_nop 0
	global_load_lds_dwordx4 v[224:225], off
	v_lshl_add_u64 v[224:225], v[234:235], 0, s[64:65]
	s_mov_b32 m0, s46
	s_nop 0
	global_load_lds_dwordx4 v[224:225], off
	s_waitcnt vmcnt(8) lgkmcnt(0)
	s_barrier
	s_setprio 1
	v_mfma_f32_16x16x32_bf16 v[62:65], v[126:129], v[190:193], v[62:65]
	v_mfma_f32_16x16x32_bf16 v[58:61], v[138:141], v[190:193], v[58:61]
	v_mfma_f32_16x16x32_bf16 v[46:49], v[126:129], v[200:203], v[46:49]
	v_mfma_f32_16x16x32_bf16 v[42:45], v[138:141], v[200:203], v[42:45]
	v_mfma_f32_16x16x32_bf16 v[30:33], v[126:129], v[208:211], v[30:33]
	v_mfma_f32_16x16x32_bf16 v[26:29], v[138:141], v[208:211], v[26:29]
	v_mfma_f32_16x16x32_bf16 v[14:17], v[126:129], v[216:219], v[14:17]
	v_mfma_f32_16x16x32_bf16 v[10:13], v[138:141], v[216:219], v[10:13]
	v_mfma_f32_16x16x32_bf16 v[62:65], v[134:137], v[194:197], v[62:65]
	v_mfma_f32_16x16x32_bf16 v[58:61], v[142:145], v[194:197], v[58:61]
	v_mfma_f32_16x16x32_bf16 v[46:49], v[134:137], v[204:207], v[46:49]
	v_mfma_f32_16x16x32_bf16 v[42:45], v[142:145], v[204:207], v[42:45]
	v_mfma_f32_16x16x32_bf16 v[30:33], v[134:137], v[212:215], v[30:33]
	v_mfma_f32_16x16x32_bf16 v[26:29], v[142:145], v[212:215], v[26:29]
	v_mfma_f32_16x16x32_bf16 v[14:17], v[134:137], v[220:223], v[14:17]
	v_mfma_f32_16x16x32_bf16 v[10:13], v[142:145], v[220:223], v[10:13]
	v_mfma_f32_16x16x32_bf16 v[54:57], v[146:149], v[190:193], v[54:57]
	v_mfma_f32_16x16x32_bf16 v[50:53], v[154:157], v[190:193], v[50:53]
	v_mfma_f32_16x16x32_bf16 v[38:41], v[146:149], v[200:203], v[38:41]
	v_mfma_f32_16x16x32_bf16 v[34:37], v[154:157], v[200:203], v[34:37]
	v_mfma_f32_16x16x32_bf16 v[22:25], v[146:149], v[208:211], v[22:25]
	v_mfma_f32_16x16x32_bf16 v[18:21], v[154:157], v[208:211], v[18:21]
	v_mfma_f32_16x16x32_bf16 v[6:9], v[146:149], v[216:219], v[6:9]
	v_mfma_f32_16x16x32_bf16 v[2:5], v[154:157], v[216:219], v[2:5]
	v_mfma_f32_16x16x32_bf16 v[54:57], v[150:153], v[194:197], v[54:57]
	v_mfma_f32_16x16x32_bf16 v[50:53], v[186:189], v[194:197], v[50:53]
	v_mfma_f32_16x16x32_bf16 v[38:41], v[150:153], v[204:207], v[38:41]
	v_mfma_f32_16x16x32_bf16 v[34:37], v[186:189], v[204:207], v[34:37]
	v_mfma_f32_16x16x32_bf16 v[22:25], v[150:153], v[212:215], v[22:25]
	v_mfma_f32_16x16x32_bf16 v[18:21], v[186:189], v[212:215], v[18:21]
	v_mfma_f32_16x16x32_bf16 v[6:9], v[150:153], v[220:223], v[6:9]
	v_mfma_f32_16x16x32_bf16 v[2:5], v[186:189], v[220:223], v[2:5]
	s_setprio 0
	s_barrier
	s_add_u32 s92, s92, 0x100
	s_addc_u32 s93, s93, 0
	s_add_u32 s18, s18, 0x100
	s_addc_u32 s19, s19, 0
	s_cmp_ge_u32 s94, s47
	s_mov_b32 s20, s94
	s_cbranch_scc0 .LBB0_778
	s_and_b64 vcc, exec, s[12:13]
	s_cbranch_vccz .LBB0_781
	s_barrier

; #define PG8_STAGE(bufoff, gbase, voff) do { _Pragma("unroll") for (int _i = 0; _i < 2; ++_i) \
;         __builtin_amdgcn_global_load_lds((const unsigned*)((const char*)(gbase) + (voff)[_i]), (LAS unsigned*)(lds + (bufoff) + ldsw + _i * 8192), 16, 0, 0); } while (0)
; #define PG8_LDA(dst, b, h) do { _Pragma("unroll") for (int m = 0; m < 4; ++m) _Pragma("unroll") for (int k = 0; k < 2; ++k) dst[m][k] = *(const LAS bf16x8*)(lds + PG8_SA(b, h) + aoff + m * 2048 + k * 1024); } while (0)
; #define PG8_LDB(dst, b, h) do { _Pragma("unroll") for (int n = 0; n < 2; ++n) _Pragma("unroll") for (int k = 0; k < 2; ++k) dst[n][k] = *(const LAS bf16x8*)(lds + PG8_SB(b, h) + boff + n * 2048 + k * 1024); } while (0)
; #define PG8_MMA(ai, bj, At, Bt) do { __builtin_amdgcn_s_setprio(1); _Pragma("unroll") for (int m = 0; m < 4; ++m) _Pragma("unroll") for (int n = 0; n < 2; ++n) _Pragma("unroll") for (int k = 0; k < 2; ++k) \
;         acc[ai][bj][m][n] = __builtin_amdgcn_mfma_f32_16x16x32_bf16(Bt[n][k], At[m][k], acc[ai][bj][m][n], 0, 0, 0); __builtin_amdgcn_s_setprio(0); } while (0)
; #define PG8_WAIT_V(n) asm volatile("s_waitcnt vmcnt(" #n ")" ::: "memory")
; #define PG8_WAIT_L(n) asm volatile("s_waitcnt lgkmcnt(" #n ")" ::: "memory")
; #define PG8_BAR __builtin_amdgcn_s_barrier()
; #define PG8_SCHED __builtin_amdgcn_sched_barrier(0)
; template <class Epi, class Sched>
; __device__ __forceinline__ void gemm_phase(LAS unsigned char* lds, const Gemm g, const Sched S, const Epi E, const int tid) {
;     ...
;         for (int t = 0; t < nt; t += 2) {
;             const bool last = (t == nt - 2);
;             const char* a1 = cA + (size_t)(t + 1) * kstep;
;             const char* a2 = last ? nA : cA + (size_t)(t + 2) * kstep; const char* b2 = last ? nB : cB + (size_t)(t + 2) * kstep;
;             const char* a3 = a2 + kstep; const char* b3 = b2 + kstep;
;             PG8_LDB(B0, 0, 0); PG8_LDB(B1, 0, 1); PG8_SCHED; PG8_LDA(At, 0, 0); PG8_STAGE(PG8_SA(1, 1), a1 + hstepA, voffA);
;             PG8_WAIT_V(8); PG8_WAIT_L(0); PG8_BAR; PG8_MMA(0, 0, At, B0); PG8_MMA(0, 1, At, B1); PG8_BAR; PG8_SCHED;
;             PG8_LDA(At, 0, 1); PG8_STAGE(PG8_SB(0, 0), b2, voffB); PG8_STAGE(PG8_SB(0, 1), b2 + hstepB, voffB); PG8_STAGE(PG8_SA(0, 0), a2, voffA);
;             PG8_WAIT_V(8); PG8_WAIT_L(0); PG8_BAR; PG8_MMA(1, 0, At, B0); PG8_MMA(1, 1, At, B1); PG8_BAR; PG8_SCHED;
.LBB0_819:
	s_add_u32 s24, s22, 0xfffc0080
	s_addc_u32 s25, s23, -1
	s_add_i32 s85, 0, 0x10000
	s_cmp_eq_u32 s84, 12
	s_cselect_b32 s27, s9, s25
	s_cselect_b32 s26, s17, s24
	s_cselect_b32 s25, s15, s83
	s_cselect_b32 s24, s69, s82
	s_add_i32 s90, 0, 0x14000
	v_add_u32_e32 v154, s85, v165
	v_add_u32_e32 v162, s90, v165
	ds_read_b128 v[98:101], v154
	ds_read_b128 v[134:137], v154 offset:1024
	ds_read_b128 v[150:153], v154 offset:2048
	ds_read_b128 v[154:157], v154 offset:3072
	ds_read_b128 v[158:161], v162
	ds_read_b128 v[180:183], v162 offset:1024
	ds_read_b128 v[184:187], v162 offset:2048
	ds_read_b128 v[188:191], v162 offset:3072
	v_lshl_add_u64 v[162:163], s[22:23], 0, v[148:149]
	s_add_i32 m0, s40, 0xc000
	ds_read_b128 v[192:195], v166
	ds_read_b128 v[196:199], v166 offset:1024
	ds_read_b128 v[200:203], v166 offset:2048
	ds_read_b128 v[204:207], v166 offset:3072
	ds_read_b128 v[208:211], v166 offset:4096
	ds_read_b128 v[212:215], v166 offset:5120
	ds_read_b128 v[216:219], v166 offset:6144
	ds_read_b128 v[220:223], v166 offset:7168
	global_load_lds_dwordx4 v[162:163], off
	v_lshl_add_u64 v[162:163], s[22:23], 0, v[146:147]
	s_add_i32 m0, s40, 0xe000
	s_nop 0
	global_load_lds_dwordx4 v[162:163], off
	s_waitcnt vmcnt(8) lgkmcnt(0)
	s_barrier
	s_setprio 1
	v_mfma_f32_16x16x32_bf16 v[130:133], v[98:101], v[192:195], v[130:133]
	v_mfma_f32_16x16x32_bf16 v[118:121], v[150:153], v[192:195], v[118:121]
	v_mfma_f32_16x16x32_bf16 v[114:117], v[98:101], v[200:203], v[114:117]
	v_mfma_f32_16x16x32_bf16 v[102:105], v[150:153], v[200:203], v[102:105]
	v_mfma_f32_16x16x32_bf16 v[94:97], v[98:101], v[208:211], v[94:97]
	v_mfma_f32_16x16x32_bf16 v[82:85], v[150:153], v[208:211], v[82:85]
	v_mfma_f32_16x16x32_bf16 v[78:81], v[98:101], v[216:219], v[78:81]
	v_mfma_f32_16x16x32_bf16 v[66:69], v[150:153], v[216:219], v[66:69]
	v_mfma_f32_16x16x32_bf16 v[130:133], v[134:137], v[196:199], v[130:133]
	v_mfma_f32_16x16x32_bf16 v[118:121], v[154:157], v[196:199], v[118:121]
	v_mfma_f32_16x16x32_bf16 v[114:117], v[134:137], v[204:207], v[114:117]
	v_mfma_f32_16x16x32_bf16 v[102:105], v[154:157], v[204:207], v[102:105]
	v_mfma_f32_16x16x32_bf16 v[94:97], v[134:137], v[212:215], v[94:97]
	v_mfma_f32_16x16x32_bf16 v[82:85], v[154:157], v[212:215], v[82:85]
	v_mfma_f32_16x16x32_bf16 v[78:81], v[134:137], v[220:223], v[78:81]
	v_mfma_f32_16x16x32_bf16 v[66:69], v[154:157], v[220:223], v[66:69]
	v_mfma_f32_16x16x32_bf16 v[126:129], v[158:161], v[192:195], v[126:129]
	v_mfma_f32_16x16x32_bf16 v[122:125], v[184:187], v[192:195], v[122:125]
	v_mfma_f32_16x16x32_bf16 v[110:113], v[158:161], v[200:203], v[110:113]
	v_mfma_f32_16x16x32_bf16 v[106:109], v[184:187], v[200:203], v[106:109]
	v_mfma_f32_16x16x32_bf16 v[90:93], v[158:161], v[208:211], v[90:93]
	v_mfma_f32_16x16x32_bf16 v[86:89], v[184:187], v[208:211], v[86:89]
	v_mfma_f32_16x16x32_bf16 v[74:77], v[158:161], v[216:219], v[74:77]
	v_mfma_f32_16x16x32_bf16 v[70:73], v[184:187], v[216:219], v[70:73]
	v_mfma_f32_16x16x32_bf16 v[126:129], v[180:183], v[196:199], v[126:129]
	v_mfma_f32_16x16x32_bf16 v[122:125], v[188:191], v[196:199], v[122:125]
	v_mfma_f32_16x16x32_bf16 v[110:113], v[180:183], v[204:207], v[110:113]
	v_mfma_f32_16x16x32_bf16 v[106:109], v[188:191], v[204:207], v[106:109]
	v_mfma_f32_16x16x32_bf16 v[90:93], v[180:183], v[212:215], v[90:93]
	v_mfma_f32_16x16x32_bf16 v[86:89], v[188:191], v[212:215], v[86:89]
	v_mfma_f32_16x16x32_bf16 v[74:77], v[180:183], v[220:223], v[74:77]
	v_mfma_f32_16x16x32_bf16 v[70:73], v[188:191], v[220:223], v[70:73]
	s_setprio 0
	s_barrier
	s_add_i32 s85, s85, s28
	v_lshl_add_u64 v[162:163], s[24:25], 0, v[142:143]
	s_mov_b32 m0, s85
	ds_read_b128 v[192:195], v166 offset:16384
	ds_read_b128 v[196:199], v166 offset:17408
	ds_read_b128 v[200:203], v166 offset:18432
	ds_read_b128 v[204:207], v166 offset:19456
	ds_read_b128 v[208:211], v166 offset:20480
	ds_read_b128 v[212:215], v166 offset:21504
	ds_read_b128 v[216:219], v166 offset:22528
	ds_read_b128 v[220:223], v166 offset:23552
	global_load_lds_dwordx4 v[162:163], off
	s_add_i32 m0, s85, 0x2000
	s_add_u32 s88, s24, 0x40000
	v_lshl_add_u64 v[224:225], s[24:25], 0, v[138:139]
	s_addc_u32 s89, s25, 0
	s_add_i32 s85, s90, s28
	global_load_lds_dwordx4 v[224:225], off
	v_lshl_add_u64 v[226:227], s[88:89], 0, v[142:143]
	s_mov_b32 m0, s85
	v_lshl_add_u64 v[228:229], s[26:27], 0, v[140:141]
	global_load_lds_dwordx4 v[226:227], off
	v_lshl_add_u64 v[226:227], s[88:89], 0, v[138:139]
	s_add_i32 m0, s85, 0x2000
	s_nop 0
	global_load_lds_dwordx4 v[226:227], off
	v_lshl_add_u64 v[226:227], s[26:27], 0, v[144:145]
	s_mov_b32 m0, s40
	s_nop 0
	global_load_lds_dwordx4 v[226:227], off
	s_mov_b32 m0, s41
	s_nop 0
	global_load_lds_dwordx4 v[228:229], off
	s_waitcnt vmcnt(8) lgkmcnt(0)
	s_barrier
; #define PG8_STAGE(bufoff, gbase, voff) do { _Pragma("unroll") for (int _i = 0; _i < 2; ++_i) \
;         __builtin_amdgcn_global_load_lds((const unsigned*)((const char*)(gbase) + (voff)[_i]), (LAS unsigned*)(lds + (bufoff) + ldsw + _i * 8192), 16, 0, 0); } while (0)
; #define PG8_LDA(dst, b, h) do { _Pragma("unroll") for (int m = 0; m < 4; ++m) _Pragma("unroll") for (int k = 0; k < 2; ++k) dst[m][k] = *(const LAS bf16x8*)(lds + PG8_SA(b, h) + aoff + m * 2048 + k * 1024); } while (0)
; #define PG8_LDB(dst, b, h) do { _Pragma("unroll") for (int n = 0; n < 2; ++n) _Pragma("unroll") for (int k = 0; k < 2; ++k) dst[n][k] = *(const LAS bf16x8*)(lds + PG8_SB(b, h) + boff + n * 2048 + k * 1024); } while (0)
; #define PG8_MMA(ai, bj, At, Bt) do { __builtin_amdgcn_s_setprio(1); _Pragma("unroll") for (int m = 0; m < 4; ++m) _Pragma("unroll") for (int n = 0; n < 2; ++n) _Pragma("unroll") for (int k = 0; k < 2; ++k) \
;         acc[ai][bj][m][n] = __builtin_amdgcn_mfma_f32_16x16x32_bf16(Bt[n][k], At[m][k], acc[ai][bj][m][n], 0, 0, 0); __builtin_amdgcn_s_setprio(0); } while (0)
; #define PG8_WAIT_V(n) asm volatile("s_waitcnt vmcnt(" #n ")" ::: "memory")
; #define PG8_WAIT_L(n) asm volatile("s_waitcnt lgkmcnt(" #n ")" ::: "memory")
; #define PG8_BAR __builtin_amdgcn_s_barrier()
; #define PG8_SCHED __builtin_amdgcn_sched_barrier(0)
; template <class Epi, class Sched>
; __device__ __forceinline__ void gemm_phase(LAS unsigned char* lds, const Gemm g, const Sched S, const Epi E, const int tid) {
;     ...
;             PG8_WAIT_V(8); PG8_WAIT_L(0); PG8_BAR; PG8_MMA(1, 0, At, B0); PG8_MMA(1, 1, At, B1); PG8_BAR; PG8_SCHED;
;             PG8_LDB(B0, 1, 0); PG8_LDB(B1, 1, 1); PG8_SCHED; PG8_LDA(At, 1, 0); PG8_STAGE(PG8_SA(0, 1), a2 + hstepA, voffA);
;             PG8_WAIT_V(8); PG8_WAIT_L(0); PG8_BAR; PG8_MMA(0, 0, At, B0); PG8_MMA(0, 1, At, B1); PG8_BAR; PG8_SCHED;
	s_setprio 1
	v_mfma_f32_16x16x32_bf16 v[62:65], v[98:101], v[192:195], v[62:65]
	v_mfma_f32_16x16x32_bf16 v[50:53], v[150:153], v[192:195], v[50:53]
	v_mfma_f32_16x16x32_bf16 v[46:49], v[98:101], v[200:203], v[46:49]
	v_mfma_f32_16x16x32_bf16 v[34:37], v[150:153], v[200:203], v[34:37]
	v_mfma_f32_16x16x32_bf16 v[30:33], v[98:101], v[208:211], v[30:33]
	v_mfma_f32_16x16x32_bf16 v[18:21], v[150:153], v[208:211], v[18:21]
	v_mfma_f32_16x16x32_bf16 v[14:17], v[98:101], v[216:219], v[14:17]
	v_mfma_f32_16x16x32_bf16 v[6:9], v[150:153], v[216:219], v[6:9]
	v_mfma_f32_16x16x32_bf16 v[62:65], v[134:137], v[196:199], v[62:65]
	v_mfma_f32_16x16x32_bf16 v[50:53], v[154:157], v[196:199], v[50:53]
	v_mfma_f32_16x16x32_bf16 v[46:49], v[134:137], v[204:207], v[46:49]
	v_mfma_f32_16x16x32_bf16 v[34:37], v[154:157], v[204:207], v[34:37]
	v_mfma_f32_16x16x32_bf16 v[30:33], v[134:137], v[212:215], v[30:33]
	v_mfma_f32_16x16x32_bf16 v[18:21], v[154:157], v[212:215], v[18:21]
	v_mfma_f32_16x16x32_bf16 v[14:17], v[134:137], v[220:223], v[14:17]
	v_mfma_f32_16x16x32_bf16 v[6:9], v[154:157], v[220:223], v[6:9]
	v_mfma_f32_16x16x32_bf16 v[58:61], v[158:161], v[192:195], v[58:61]
	v_mfma_f32_16x16x32_bf16 v[54:57], v[184:187], v[192:195], v[54:57]
	v_mfma_f32_16x16x32_bf16 v[42:45], v[158:161], v[200:203], v[42:45]
	v_mfma_f32_16x16x32_bf16 v[38:41], v[184:187], v[200:203], v[38:41]
	v_mfma_f32_16x16x32_bf16 v[26:29], v[158:161], v[208:211], v[26:29]
	v_mfma_f32_16x16x32_bf16 v[22:25], v[184:187], v[208:211], v[22:25]
	v_mfma_f32_16x16x32_bf16 v[10:13], v[158:161], v[216:219], v[10:13]
	v_mfma_f32_16x16x32_bf16 v[2:5], v[184:187], v[216:219], v[2:5]
	v_mfma_f32_16x16x32_bf16 v[58:61], v[180:183], v[196:199], v[58:61]
	v_mfma_f32_16x16x32_bf16 v[54:57], v[188:191], v[196:199], v[54:57]
	v_mfma_f32_16x16x32_bf16 v[42:45], v[180:183], v[204:207], v[42:45]
	v_mfma_f32_16x16x32_bf16 v[38:41], v[188:191], v[204:207], v[38:41]
	v_mfma_f32_16x16x32_bf16 v[26:29], v[180:183], v[212:215], v[26:29]
	v_mfma_f32_16x16x32_bf16 v[22:25], v[188:191], v[212:215], v[22:25]
	v_mfma_f32_16x16x32_bf16 v[10:13], v[180:183], v[220:223], v[10:13]
	v_mfma_f32_16x16x32_bf16 v[2:5], v[188:191], v[220:223], v[2:5]
	s_setprio 0
	s_barrier
	s_add_i32 s85, 0, 0x18000
	s_add_i32 s88, 0, 0x1c000
	v_add_u32_e32 v154, s85, v165
	v_add_u32_e32 v167, s88, v165
	ds_read_b128 v[98:101], v154
	ds_read_b128 v[134:137], v154 offset:1024
	ds_read_b128 v[150:153], v154 offset:2048
	ds_read_b128 v[154:157], v154 offset:3072
	ds_read_b128 v[158:161], v167
	ds_read_b128 v[180:183], v167 offset:1024
	ds_read_b128 v[184:187], v167 offset:2048
	ds_read_b128 v[188:191], v167 offset:3072
	s_add_u32 s26, s26, 0x40000
	s_addc_u32 s27, s27, 0
	s_mov_b32 m0, s42
	v_lshl_add_u64 v[230:231], s[26:27], 0, v[144:145]
	ds_read_b128 v[192:195], v166 offset:32768
	ds_read_b128 v[196:199], v166 offset:33792
	ds_read_b128 v[200:203], v166 offset:34816
	ds_read_b128 v[204:207], v166 offset:35840
	ds_read_b128 v[208:211], v166 offset:36864
	ds_read_b128 v[212:215], v166 offset:37888
	ds_read_b128 v[216:219], v166 offset:38912
	ds_read_b128 v[220:223], v166 offset:39936
	global_load_lds_dwordx4 v[230:231], off
	v_lshl_add_u64 v[230:231], s[26:27], 0, v[140:141]
	s_mov_b32 m0, s43
	s_nop 0
	global_load_lds_dwordx4 v[230:231], off
	s_waitcnt vmcnt(8) lgkmcnt(0)
	s_barrier
	s_setprio 1
	v_mfma_f32_16x16x32_bf16 v[130:133], v[98:101], v[192:195], v[130:133]
	v_mfma_f32_16x16x32_bf16 v[118:121], v[150:153], v[192:195], v[118:121]
	v_mfma_f32_16x16x32_bf16 v[114:117], v[98:101], v[200:203], v[114:117]
	v_mfma_f32_16x16x32_bf16 v[102:105], v[150:153], v[200:203], v[102:105]
	v_mfma_f32_16x16x32_bf16 v[94:97], v[98:101], v[208:211], v[94:97]
	v_mfma_f32_16x16x32_bf16 v[82:85], v[150:153], v[208:211], v[82:85]
	v_mfma_f32_16x16x32_bf16 v[78:81], v[98:101], v[216:219], v[78:81]
	v_mfma_f32_16x16x32_bf16 v[66:69], v[150:153], v[216:219], v[66:69]
	v_mfma_f32_16x16x32_bf16 v[130:133], v[134:137], v[196:199], v[130:133]
	v_mfma_f32_16x16x32_bf16 v[118:121], v[154:157], v[196:199], v[118:121]
	v_mfma_f32_16x16x32_bf16 v[114:117], v[134:137], v[204:207], v[114:117]
	v_mfma_f32_16x16x32_bf16 v[102:105], v[154:157], v[204:207], v[102:105]
	v_mfma_f32_16x16x32_bf16 v[94:97], v[134:137], v[212:215], v[94:97]
	v_mfma_f32_16x16x32_bf16 v[82:85], v[154:157], v[212:215], v[82:85]
	v_mfma_f32_16x16x32_bf16 v[78:81], v[134:137], v[220:223], v[78:81]
	v_mfma_f32_16x16x32_bf16 v[66:69], v[154:157], v[220:223], v[66:69]
	v_mfma_f32_16x16x32_bf16 v[126:129], v[158:161], v[192:195], v[126:129]
	v_mfma_f32_16x16x32_bf16 v[122:125], v[184:187], v[192:195], v[122:125]
	v_mfma_f32_16x16x32_bf16 v[110:113], v[158:161], v[200:203], v[110:113]
	v_mfma_f32_16x16x32_bf16 v[106:109], v[184:187], v[200:203], v[106:109]
	v_mfma_f32_16x16x32_bf16 v[90:93], v[158:161], v[208:211], v[90:93]
	v_mfma_f32_16x16x32_bf16 v[86:89], v[184:187], v[208:211], v[86:89]
	v_mfma_f32_16x16x32_bf16 v[74:77], v[158:161], v[216:219], v[74:77]
	v_mfma_f32_16x16x32_bf16 v[70:73], v[184:187], v[216:219], v[70:73]
	v_mfma_f32_16x16x32_bf16 v[126:129], v[180:183], v[196:199], v[126:129]
	v_mfma_f32_16x16x32_bf16 v[122:125], v[188:191], v[196:199], v[122:125]
	v_mfma_f32_16x16x32_bf16 v[110:113], v[180:183], v[204:207], v[110:113]
	v_mfma_f32_16x16x32_bf16 v[106:109], v[188:191], v[204:207], v[106:109]
	v_mfma_f32_16x16x32_bf16 v[90:93], v[180:183], v[212:215], v[90:93]
	v_mfma_f32_16x16x32_bf16 v[86:89], v[188:191], v[212:215], v[86:89]
	v_mfma_f32_16x16x32_bf16 v[74:77], v[180:183], v[220:223], v[74:77]
	v_mfma_f32_16x16x32_bf16 v[70:73], v[188:191], v[220:223], v[70:73]
	s_setprio 0
	s_barrier
; #define PG8_STAGE(bufoff, gbase, voff) do { _Pragma("unroll") for (int _i = 0; _i < 2; ++_i) \
;         __builtin_amdgcn_global_load_lds((const unsigned*)((const char*)(gbase) + (voff)[_i]), (LAS unsigned*)(lds + (bufoff) + ldsw + _i * 8192), 16, 0, 0); } while (0)
; #define PG8_LDA(dst, b, h) do { _Pragma("unroll") for (int m = 0; m < 4; ++m) _Pragma("unroll") for (int k = 0; k < 2; ++k) dst[m][k] = *(const LAS bf16x8*)(lds + PG8_SA(b, h) + aoff + m * 2048 + k * 1024); } while (0)
; #define PG8_MMA(ai, bj, At, Bt) do { __builtin_amdgcn_s_setprio(1); _Pragma("unroll") for (int m = 0; m < 4; ++m) _Pragma("unroll") for (int n = 0; n < 2; ++n) _Pragma("unroll") for (int k = 0; k < 2; ++k) \
;         acc[ai][bj][m][n] = __builtin_amdgcn_mfma_f32_16x16x32_bf16(Bt[n][k], At[m][k], acc[ai][bj][m][n], 0, 0, 0); __builtin_amdgcn_s_setprio(0); } while (0)
; #define PG8_WAIT_V(n) asm volatile("s_waitcnt vmcnt(" #n ")" ::: "memory")
; #define PG8_WAIT_L(n) asm volatile("s_waitcnt lgkmcnt(" #n ")" ::: "memory")
; #define PG8_BAR __builtin_amdgcn_s_barrier()
; #define PG8_SCHED __builtin_amdgcn_sched_barrier(0)
; template <class Epi, class Sched>
; __device__ __forceinline__ void gemm_phase(LAS unsigned char* lds, const Gemm g, const Sched S, const Epi E, const int tid) {
;     ...
;             PG8_LDA(At, 1, 1); PG8_STAGE(PG8_SB(1, 0), b3, voffB); PG8_STAGE(PG8_SB(1, 1), b3 + hstepB, voffB); PG8_STAGE(PG8_SA(1, 0), a3, voffA);
;             PG8_WAIT_V(8); PG8_WAIT_L(0); PG8_BAR; PG8_MMA(1, 0, At, B0); PG8_MMA(1, 1, At, B1); PG8_BAR; PG8_SCHED;
;         }
	s_add_i32 s26, s85, s28
	v_lshl_add_u64 v[162:163], v[162:163], 0, s[64:65]
	s_mov_b32 m0, s26
	ds_read_b128 v[192:195], v166 offset:49152
	ds_read_b128 v[196:199], v166 offset:50176
	ds_read_b128 v[200:203], v166 offset:51200
	ds_read_b128 v[204:207], v166 offset:52224
	ds_read_b128 v[208:211], v166 offset:53248
	ds_read_b128 v[212:215], v166 offset:54272
	ds_read_b128 v[216:219], v166 offset:55296
	ds_read_b128 v[220:223], v166 offset:56320
	global_load_lds_dwordx4 v[162:163], off
	s_add_i32 m0, s26, 0x2000
	s_add_u32 s24, s24, 0x40080
	v_lshl_add_u64 v[162:163], v[224:225], 0, s[64:65]
	s_addc_u32 s25, s25, 0
	s_add_i32 s26, s88, s28
	global_load_lds_dwordx4 v[162:163], off
	v_lshl_add_u64 v[162:163], s[24:25], 0, v[142:143]
	s_mov_b32 m0, s26
	s_nop 0
	global_load_lds_dwordx4 v[162:163], off
	v_lshl_add_u64 v[162:163], s[24:25], 0, v[138:139]
	s_add_i32 m0, s26, 0x2000
	s_nop 0
	global_load_lds_dwordx4 v[162:163], off
	v_lshl_add_u64 v[162:163], v[226:227], 0, s[64:65]
	s_mov_b32 m0, s46
	s_nop 0
	global_load_lds_dwordx4 v[162:163], off
	v_lshl_add_u64 v[162:163], v[228:229], 0, s[64:65]
	s_mov_b32 m0, s47
	s_nop 0
	global_load_lds_dwordx4 v[162:163], off
	s_waitcnt vmcnt(8) lgkmcnt(0)
	s_barrier
	s_setprio 1
	v_mfma_f32_16x16x32_bf16 v[62:65], v[98:101], v[192:195], v[62:65]
	v_mfma_f32_16x16x32_bf16 v[50:53], v[150:153], v[192:195], v[50:53]
	v_mfma_f32_16x16x32_bf16 v[46:49], v[98:101], v[200:203], v[46:49]
	v_mfma_f32_16x16x32_bf16 v[34:37], v[150:153], v[200:203], v[34:37]
	v_mfma_f32_16x16x32_bf16 v[30:33], v[98:101], v[208:211], v[30:33]
	v_mfma_f32_16x16x32_bf16 v[18:21], v[150:153], v[208:211], v[18:21]
	v_mfma_f32_16x16x32_bf16 v[14:17], v[98:101], v[216:219], v[14:17]
	v_mfma_f32_16x16x32_bf16 v[6:9], v[150:153], v[216:219], v[6:9]
	v_mfma_f32_16x16x32_bf16 v[62:65], v[134:137], v[196:199], v[62:65]
	v_mfma_f32_16x16x32_bf16 v[50:53], v[154:157], v[196:199], v[50:53]
	v_mfma_f32_16x16x32_bf16 v[46:49], v[134:137], v[204:207], v[46:49]
	v_mfma_f32_16x16x32_bf16 v[34:37], v[154:157], v[204:207], v[34:37]
	v_mfma_f32_16x16x32_bf16 v[30:33], v[134:137], v[212:215], v[30:33]
	v_mfma_f32_16x16x32_bf16 v[18:21], v[154:157], v[212:215], v[18:21]
	v_mfma_f32_16x16x32_bf16 v[14:17], v[134:137], v[220:223], v[14:17]
	v_mfma_f32_16x16x32_bf16 v[6:9], v[154:157], v[220:223], v[6:9]
	v_mfma_f32_16x16x32_bf16 v[58:61], v[158:161], v[192:195], v[58:61]
	v_mfma_f32_16x16x32_bf16 v[54:57], v[184:187], v[192:195], v[54:57]
	v_mfma_f32_16x16x32_bf16 v[42:45], v[158:161], v[200:203], v[42:45]
	v_mfma_f32_16x16x32_bf16 v[38:41], v[184:187], v[200:203], v[38:41]
	v_mfma_f32_16x16x32_bf16 v[26:29], v[158:161], v[208:211], v[26:29]
	v_mfma_f32_16x16x32_bf16 v[22:25], v[184:187], v[208:211], v[22:25]
	v_mfma_f32_16x16x32_bf16 v[10:13], v[158:161], v[216:219], v[10:13]
	v_mfma_f32_16x16x32_bf16 v[2:5], v[184:187], v[216:219], v[2:5]
	v_mfma_f32_16x16x32_bf16 v[58:61], v[180:183], v[196:199], v[58:61]
	v_mfma_f32_16x16x32_bf16 v[54:57], v[188:191], v[196:199], v[54:57]
	v_mfma_f32_16x16x32_bf16 v[42:45], v[180:183], v[204:207], v[42:45]
	v_mfma_f32_16x16x32_bf16 v[38:41], v[188:191], v[204:207], v[38:41]
	v_mfma_f32_16x16x32_bf16 v[26:29], v[180:183], v[212:215], v[26:29]
	v_mfma_f32_16x16x32_bf16 v[22:25], v[188:191], v[212:215], v[22:25]
	v_mfma_f32_16x16x32_bf16 v[10:13], v[180:183], v[220:223], v[10:13]
	v_mfma_f32_16x16x32_bf16 v[2:5], v[188:191], v[220:223], v[2:5]
	s_setprio 0
	s_barrier
	s_add_i32 s84, s84, 2
	s_add_u32 s82, s82, 0x100
	s_addc_u32 s83, s83, 0
	s_add_u32 s22, s22, 0x100
	s_addc_u32 s23, s23, 0
	s_cmp_gt_u32 s84, 13
	s_cbranch_scc0 .LBB0_819
	s_and_b64 vcc, exec, s[12:13]
	s_cbranch_vccz .LBB0_822
	s_barrier
